# GEMM K-loops (FFN up/down x2, w_in): first iteration peeled with C=0 MFMAs, per-tile 128 v_mov accumulator zeroing removed
# speedup vs baseline: 1.0169x; 1.0001x over previous
; #define PG8_STAGE(bufoff, gbase, voff) do { _Pragma("unroll") for (int _i = 0; _i < 2; ++_i) \
;         __builtin_amdgcn_global_load_lds((const unsigned*)((const char*)(gbase) + (voff)[_i]), (PG8_LAS unsigned*)(lds + (bufoff) + ldsw + _i * 8192), 16, 0, 0); } while (0)
; #define PG8_LDA(dst, b, h) do { _Pragma("unroll") for (int m = 0; m < 4; ++m) _Pragma("unroll") for (int k = 0; k < 2; ++k) dst[m][k] = *(const PG8_LAS bf16x8*)(lds + PG8_SA(b, h) + aoff + m * 2048 + k * 1024); } while (0)
; #define PG8_LDB(dst, b, h) do { _Pragma("unroll") for (int n = 0; n < 2; ++n) _Pragma("unroll") for (int k = 0; k < 2; ++k) dst[n][k] = *(const PG8_LAS bf16x8*)(lds + PG8_SB(b, h) + boff + n * 2048 + k * 1024); } while (0)
; #define PG8_MMA(ai, bj, At, Bt) do { __builtin_amdgcn_s_setprio(1); _Pragma("unroll") for (int m = 0; m < 4; ++m) _Pragma("unroll") for (int n = 0; n < 2; ++n) _Pragma("unroll") for (int k = 0; k < 2; ++k) \
;         acc[ai][bj][m][n] = __builtin_amdgcn_mfma_f32_16x16x32_bf16(Bt[n][k], At[m][k], acc[ai][bj][m][n], 0, 0, 0); __builtin_amdgcn_s_setprio(0); } while (0)
; #define PG8_WAIT_V(n) asm volatile("s_waitcnt vmcnt(" #n ")" ::: "memory")
; #define PG8_WAIT_L(n) asm volatile("s_waitcnt lgkmcnt(" #n ")" ::: "memory")
; #define PG8_BAR __builtin_amdgcn_s_barrier()
; #define PG8_SCHED __builtin_amdgcn_sched_barrier(0)
; template <class Epi, class Sched, bool ALIGN_EPI = false, bool SP2 = false, bool ABLK = false>
; __device__ __forceinline__ void gemm_phase(PG8_LAS unsigned char* lds, const Gemm g, const Sched& S, const Epi& E) {
;     ...
;             PG8_LDB(B0, 0, 0); PG8_LDB(B1, 0, 1); PG8_SCHED; PG8_LDA(At, 0, 0); PG8_STAGE(PG8_SA(1, 1), a1 + hstepA, voffA);
;             PG8_WAIT_V(8); PG8_WAIT_L(0); PG8_BAR; PG8_MMA(0, 0, At, B0); PG8_MMA(0, 1, At, B1); PG8_BAR; PG8_SCHED;
;             PG8_LDA(At, 0, 1); PG8_STAGE(PG8_SB(0, 0), b2, voffB); PG8_STAGE(PG8_SB(0, 1), b2 + hstep, voffB); PG8_STAGE(PG8_SA(0, 0), a2, voffA);
;             PG8_WAIT_V(8); PG8_WAIT_L(0); PG8_BAR; PG8_MMA(1, 0, At, B0); PG8_MMA(1, 1, At, B1); PG8_BAR; PG8_SCHED;
;     ...
; #pragma unroll
;         for (int a = 0; a < 2; ++a)
; #pragma unroll
;             for (int b = 0; b < 2; ++b)
; #pragma unroll
;                 for (int m = 0; m < 4; ++m)
; #pragma unroll
;                     for (int n = 0; n < 2; ++n) acc[a][b][m][n] = (f32x4){0.f, 0.f, 0.f, 0.f};
.LBB0_175:
	ds_read_b128 v[162:165], v159
	ds_read_b128 v[168:171], v159 offset:1024
	ds_read_b128 v[172:175], v159 offset:2048
	ds_read_b128 v[176:179], v159 offset:3072
	ds_read_b128 v[180:183], v160
	ds_read_b128 v[184:187], v160 offset:1024
	ds_read_b128 v[188:191], v160 offset:2048
	ds_read_b128 v[192:195], v160 offset:3072
	s_add_u32 s26, s24, 0xfffc0080
	s_addc_u32 s27, s25, -1
	s_cmp_eq_u32 s51, 12
	s_cselect_b32 s29, s17, s27
	s_cselect_b32 s28, s47, s26
	s_cselect_b32 s27, s15, s50
	s_cselect_b32 s26, s48, s49
	v_lshl_add_u64 v[156:157], s[24:25], 0, v[148:149]
	s_add_i32 m0, s23, 0xc000
	ds_read_b128 v[196:199], v161
	ds_read_b128 v[200:203], v161 offset:1024
	ds_read_b128 v[204:207], v161 offset:2048
	ds_read_b128 v[208:211], v161 offset:3072
	ds_read_b128 v[212:215], v161 offset:4096
	ds_read_b128 v[216:219], v161 offset:5120
	ds_read_b128 v[220:223], v161 offset:6144
	ds_read_b128 v[224:227], v161 offset:7168
	global_load_lds_dwordx4 v[156:157], off
	v_lshl_add_u64 v[156:157], s[24:25], 0, v[150:151]
	s_add_i32 m0, s23, 0xe000
	s_nop 0
	global_load_lds_dwordx4 v[156:157], off
	s_waitcnt vmcnt(8)
	s_waitcnt lgkmcnt(0)
	s_barrier
	s_setprio 1
	s_waitcnt lgkmcnt(0)
	v_mfma_f32_16x16x32_bf16 v[124:127], v[162:165], v[196:199], 0
	v_mfma_f32_16x16x32_bf16 v[120:123], v[172:175], v[196:199], 0
	v_mfma_f32_16x16x32_bf16 v[108:111], v[162:165], v[204:207], 0
	v_mfma_f32_16x16x32_bf16 v[104:107], v[172:175], v[204:207], 0
	v_mfma_f32_16x16x32_bf16 v[92:95], v[162:165], v[212:215], 0
	v_mfma_f32_16x16x32_bf16 v[88:91], v[172:175], v[212:215], 0
	v_mfma_f32_16x16x32_bf16 v[76:79], v[162:165], v[220:223], 0
	v_mfma_f32_16x16x32_bf16 v[72:75], v[172:175], v[220:223], 0
	v_mfma_f32_16x16x32_bf16 v[124:127], v[168:171], v[200:203], v[124:127]
	v_mfma_f32_16x16x32_bf16 v[120:123], v[176:179], v[200:203], v[120:123]
	v_mfma_f32_16x16x32_bf16 v[108:111], v[168:171], v[208:211], v[108:111]
	v_mfma_f32_16x16x32_bf16 v[104:107], v[176:179], v[208:211], v[104:107]
	v_mfma_f32_16x16x32_bf16 v[92:95], v[168:171], v[216:219], v[92:95]
	v_mfma_f32_16x16x32_bf16 v[88:91], v[176:179], v[216:219], v[88:91]
	v_mfma_f32_16x16x32_bf16 v[76:79], v[168:171], v[224:227], v[76:79]
	v_mfma_f32_16x16x32_bf16 v[72:75], v[176:179], v[224:227], v[72:75]
	s_setprio 0
	s_setprio 1
	v_mfma_f32_16x16x32_bf16 v[116:119], v[180:183], v[196:199], 0
	v_mfma_f32_16x16x32_bf16 v[112:115], v[188:191], v[196:199], 0
	v_mfma_f32_16x16x32_bf16 v[100:103], v[180:183], v[204:207], 0
	v_mfma_f32_16x16x32_bf16 v[96:99], v[188:191], v[204:207], 0
	v_mfma_f32_16x16x32_bf16 v[84:87], v[180:183], v[212:215], 0
	v_mfma_f32_16x16x32_bf16 v[80:83], v[188:191], v[212:215], 0
	v_mfma_f32_16x16x32_bf16 v[68:71], v[180:183], v[220:223], 0
	v_mfma_f32_16x16x32_bf16 v[64:67], v[188:191], v[220:223], 0
	v_mfma_f32_16x16x32_bf16 v[116:119], v[184:187], v[200:203], v[116:119]
	v_mfma_f32_16x16x32_bf16 v[112:115], v[192:195], v[200:203], v[112:115]
	v_mfma_f32_16x16x32_bf16 v[100:103], v[184:187], v[208:211], v[100:103]
	v_mfma_f32_16x16x32_bf16 v[96:99], v[192:195], v[208:211], v[96:99]
	v_mfma_f32_16x16x32_bf16 v[84:87], v[184:187], v[216:219], v[84:87]
	v_mfma_f32_16x16x32_bf16 v[80:83], v[192:195], v[216:219], v[80:83]
	v_mfma_f32_16x16x32_bf16 v[68:71], v[184:187], v[224:227], v[68:71]
	v_mfma_f32_16x16x32_bf16 v[64:67], v[192:195], v[224:227], v[64:67]
	s_setprio 0
	s_barrier
	s_add_i32 s53, s43, s30
	v_lshl_add_u64 v[156:157], s[26:27], 0, v[132:133]
	s_mov_b32 m0, s53
	ds_read_b128 v[196:199], v161 offset:16384
	ds_read_b128 v[200:203], v161 offset:17408
	ds_read_b128 v[204:207], v161 offset:18432
	ds_read_b128 v[208:211], v161 offset:19456
	ds_read_b128 v[212:215], v161 offset:20480
	ds_read_b128 v[216:219], v161 offset:21504
	ds_read_b128 v[220:223], v161 offset:22528
	ds_read_b128 v[224:227], v161 offset:23552
	global_load_lds_dwordx4 v[156:157], off
	s_add_i32 m0, s53, 0x2000
	s_add_u32 s54, s26, 0x40000
	v_lshl_add_u64 v[228:229], s[26:27], 0, v[128:129]
	s_addc_u32 s55, s27, 0
	s_add_i32 s53, s44, s30
	global_load_lds_dwordx4 v[228:229], off
	v_lshl_add_u64 v[230:231], s[54:55], 0, v[132:133]
	s_mov_b32 m0, s53
	v_lshl_add_u64 v[232:233], s[28:29], 0, v[130:131]
	global_load_lds_dwordx4 v[230:231], off
	v_lshl_add_u64 v[230:231], s[54:55], 0, v[128:129]
	s_add_i32 m0, s53, 0x2000
	s_nop 0
	global_load_lds_dwordx4 v[230:231], off
	v_lshl_add_u64 v[230:231], s[28:29], 0, v[134:135]
	s_mov_b32 m0, s23
	s_nop 0
	global_load_lds_dwordx4 v[230:231], off
	s_mov_b32 m0, s34
	s_nop 0
	global_load_lds_dwordx4 v[232:233], off
	s_waitcnt vmcnt(8)
	s_waitcnt lgkmcnt(0)
	s_barrier
; #define PG8_STAGE(bufoff, gbase, voff) do { _Pragma("unroll") for (int _i = 0; _i < 2; ++_i) \
;         __builtin_amdgcn_global_load_lds((const unsigned*)((const char*)(gbase) + (voff)[_i]), (PG8_LAS unsigned*)(lds + (bufoff) + ldsw + _i * 8192), 16, 0, 0); } while (0)
; #define PG8_LDA(dst, b, h) do { _Pragma("unroll") for (int m = 0; m < 4; ++m) _Pragma("unroll") for (int k = 0; k < 2; ++k) dst[m][k] = *(const PG8_LAS bf16x8*)(lds + PG8_SA(b, h) + aoff + m * 2048 + k * 1024); } while (0)
; #define PG8_LDB(dst, b, h) do { _Pragma("unroll") for (int n = 0; n < 2; ++n) _Pragma("unroll") for (int k = 0; k < 2; ++k) dst[n][k] = *(const PG8_LAS bf16x8*)(lds + PG8_SB(b, h) + boff + n * 2048 + k * 1024); } while (0)
; #define PG8_MMA(ai, bj, At, Bt) do { __builtin_amdgcn_s_setprio(1); _Pragma("unroll") for (int m = 0; m < 4; ++m) _Pragma("unroll") for (int n = 0; n < 2; ++n) _Pragma("unroll") for (int k = 0; k < 2; ++k) \
;         acc[ai][bj][m][n] = __builtin_amdgcn_mfma_f32_16x16x32_bf16(Bt[n][k], At[m][k], acc[ai][bj][m][n], 0, 0, 0); __builtin_amdgcn_s_setprio(0); } while (0)
; #define PG8_WAIT_V(n) asm volatile("s_waitcnt vmcnt(" #n ")" ::: "memory")
; #define PG8_WAIT_L(n) asm volatile("s_waitcnt lgkmcnt(" #n ")" ::: "memory")
; #define PG8_BAR __builtin_amdgcn_s_barrier()
; #define PG8_SCHED __builtin_amdgcn_sched_barrier(0)
; template <class Epi, class Sched, bool ALIGN_EPI = false, bool SP2 = false, bool ABLK = false>
; __device__ __forceinline__ void gemm_phase(PG8_LAS unsigned char* lds, const Gemm g, const Sched& S, const Epi& E) {
;     ...
;             PG8_WAIT_V(8); PG8_WAIT_L(0); PG8_BAR; PG8_MMA(1, 0, At, B0); PG8_MMA(1, 1, At, B1); PG8_BAR; PG8_SCHED;
;             PG8_LDB(B0, 1, 0); PG8_LDB(B1, 1, 1); PG8_SCHED; PG8_LDA(At, 1, 0); PG8_STAGE(PG8_SA(0, 1), a2 + hstepA, voffA);
;             PG8_WAIT_V(8); PG8_WAIT_L(0); PG8_BAR; PG8_MMA(0, 0, At, B0); PG8_MMA(0, 1, At, B1); PG8_BAR; PG8_SCHED;
	s_setprio 1
	s_waitcnt lgkmcnt(0)
	v_mfma_f32_16x16x32_bf16 v[60:63], v[162:165], v[196:199], 0
	v_mfma_f32_16x16x32_bf16 v[56:59], v[172:175], v[196:199], 0
	v_mfma_f32_16x16x32_bf16 v[44:47], v[162:165], v[204:207], 0
	v_mfma_f32_16x16x32_bf16 v[40:43], v[172:175], v[204:207], 0
	v_mfma_f32_16x16x32_bf16 v[28:31], v[162:165], v[212:215], 0
	v_mfma_f32_16x16x32_bf16 v[24:27], v[172:175], v[212:215], 0
	v_mfma_f32_16x16x32_bf16 v[12:15], v[162:165], v[220:223], 0
	v_mfma_f32_16x16x32_bf16 v[8:11], v[172:175], v[220:223], 0
	v_mfma_f32_16x16x32_bf16 v[60:63], v[168:171], v[200:203], v[60:63]
	v_mfma_f32_16x16x32_bf16 v[56:59], v[176:179], v[200:203], v[56:59]
	v_mfma_f32_16x16x32_bf16 v[44:47], v[168:171], v[208:211], v[44:47]
	v_mfma_f32_16x16x32_bf16 v[40:43], v[176:179], v[208:211], v[40:43]
	v_mfma_f32_16x16x32_bf16 v[28:31], v[168:171], v[216:219], v[28:31]
	v_mfma_f32_16x16x32_bf16 v[24:27], v[176:179], v[216:219], v[24:27]
	v_mfma_f32_16x16x32_bf16 v[12:15], v[168:171], v[224:227], v[12:15]
	v_mfma_f32_16x16x32_bf16 v[8:11], v[176:179], v[224:227], v[8:11]
	s_setprio 0
	s_setprio 1
	v_mfma_f32_16x16x32_bf16 v[52:55], v[180:183], v[196:199], 0
	v_mfma_f32_16x16x32_bf16 v[48:51], v[188:191], v[196:199], 0
	v_mfma_f32_16x16x32_bf16 v[36:39], v[180:183], v[204:207], 0
	v_mfma_f32_16x16x32_bf16 v[32:35], v[188:191], v[204:207], 0
	v_mfma_f32_16x16x32_bf16 v[20:23], v[180:183], v[212:215], 0
	v_mfma_f32_16x16x32_bf16 v[16:19], v[188:191], v[212:215], 0
	v_mfma_f32_16x16x32_bf16 v[4:7], v[180:183], v[220:223], 0
	v_mfma_f32_16x16x32_bf16 v[0:3], v[188:191], v[220:223], 0
	v_mfma_f32_16x16x32_bf16 v[52:55], v[184:187], v[200:203], v[52:55]
	v_mfma_f32_16x16x32_bf16 v[48:51], v[192:195], v[200:203], v[48:51]
	v_mfma_f32_16x16x32_bf16 v[36:39], v[184:187], v[208:211], v[36:39]
	v_mfma_f32_16x16x32_bf16 v[32:35], v[192:195], v[208:211], v[32:35]
	v_mfma_f32_16x16x32_bf16 v[20:23], v[184:187], v[216:219], v[20:23]
	v_mfma_f32_16x16x32_bf16 v[16:19], v[192:195], v[216:219], v[16:19]
	v_mfma_f32_16x16x32_bf16 v[4:7], v[184:187], v[224:227], v[4:7]
	v_mfma_f32_16x16x32_bf16 v[0:3], v[192:195], v[224:227], v[0:3]
	s_setprio 0
	s_barrier
	s_add_i32 s53, 0, 0x18000
	v_add_u32_e32 v167, s53, v158
	s_add_i32 s54, 0, 0x1c000
	ds_read_b128 v[162:165], v167
	ds_read_b128 v[168:171], v167 offset:1024
	ds_read_b128 v[172:175], v167 offset:2048
	ds_read_b128 v[176:179], v167 offset:3072
	v_add_u32_e32 v167, s54, v158
	ds_read_b128 v[180:183], v167
	ds_read_b128 v[184:187], v167 offset:1024
	ds_read_b128 v[188:191], v167 offset:2048
	ds_read_b128 v[192:195], v167 offset:3072
	s_add_u32 s28, s28, 0x40000
	s_addc_u32 s29, s29, 0
	s_mov_b32 m0, s35
	v_lshl_add_u64 v[234:235], s[28:29], 0, v[134:135]
	ds_read_b128 v[196:199], v161 offset:32768
	ds_read_b128 v[200:203], v161 offset:33792
	ds_read_b128 v[204:207], v161 offset:34816
	ds_read_b128 v[208:211], v161 offset:35840
	ds_read_b128 v[212:215], v161 offset:36864
	ds_read_b128 v[216:219], v161 offset:37888
	ds_read_b128 v[220:223], v161 offset:38912
	ds_read_b128 v[224:227], v161 offset:39936
	global_load_lds_dwordx4 v[234:235], off
	v_lshl_add_u64 v[234:235], s[28:29], 0, v[130:131]
	s_mov_b32 m0, s38
	s_nop 0
	global_load_lds_dwordx4 v[234:235], off
	s_waitcnt vmcnt(8)
	s_waitcnt lgkmcnt(0)
	s_barrier
	s_setprio 1
	s_waitcnt lgkmcnt(0)
	v_mfma_f32_16x16x32_bf16 v[124:127], v[162:165], v[196:199], v[124:127]
	v_mfma_f32_16x16x32_bf16 v[120:123], v[172:175], v[196:199], v[120:123]
	v_mfma_f32_16x16x32_bf16 v[108:111], v[162:165], v[204:207], v[108:111]
	v_mfma_f32_16x16x32_bf16 v[104:107], v[172:175], v[204:207], v[104:107]
	v_mfma_f32_16x16x32_bf16 v[92:95], v[162:165], v[212:215], v[92:95]
	v_mfma_f32_16x16x32_bf16 v[88:91], v[172:175], v[212:215], v[88:91]
	v_mfma_f32_16x16x32_bf16 v[76:79], v[162:165], v[220:223], v[76:79]
	v_mfma_f32_16x16x32_bf16 v[72:75], v[172:175], v[220:223], v[72:75]
	v_mfma_f32_16x16x32_bf16 v[124:127], v[168:171], v[200:203], v[124:127]
	v_mfma_f32_16x16x32_bf16 v[120:123], v[176:179], v[200:203], v[120:123]
	v_mfma_f32_16x16x32_bf16 v[108:111], v[168:171], v[208:211], v[108:111]
	v_mfma_f32_16x16x32_bf16 v[104:107], v[176:179], v[208:211], v[104:107]
	v_mfma_f32_16x16x32_bf16 v[92:95], v[168:171], v[216:219], v[92:95]
	v_mfma_f32_16x16x32_bf16 v[88:91], v[176:179], v[216:219], v[88:91]
	v_mfma_f32_16x16x32_bf16 v[76:79], v[168:171], v[224:227], v[76:79]
	v_mfma_f32_16x16x32_bf16 v[72:75], v[176:179], v[224:227], v[72:75]
	s_setprio 0
	s_setprio 1
	v_mfma_f32_16x16x32_bf16 v[116:119], v[180:183], v[196:199], v[116:119]
	v_mfma_f32_16x16x32_bf16 v[112:115], v[188:191], v[196:199], v[112:115]
	v_mfma_f32_16x16x32_bf16 v[100:103], v[180:183], v[204:207], v[100:103]
	v_mfma_f32_16x16x32_bf16 v[96:99], v[188:191], v[204:207], v[96:99]
	v_mfma_f32_16x16x32_bf16 v[84:87], v[180:183], v[212:215], v[84:87]
	v_mfma_f32_16x16x32_bf16 v[80:83], v[188:191], v[212:215], v[80:83]
	v_mfma_f32_16x16x32_bf16 v[68:71], v[180:183], v[220:223], v[68:71]
	v_mfma_f32_16x16x32_bf16 v[64:67], v[188:191], v[220:223], v[64:67]
	v_mfma_f32_16x16x32_bf16 v[116:119], v[184:187], v[200:203], v[116:119]
	v_mfma_f32_16x16x32_bf16 v[112:115], v[192:195], v[200:203], v[112:115]
	v_mfma_f32_16x16x32_bf16 v[100:103], v[184:187], v[208:211], v[100:103]
	v_mfma_f32_16x16x32_bf16 v[96:99], v[192:195], v[208:211], v[96:99]
	v_mfma_f32_16x16x32_bf16 v[84:87], v[184:187], v[216:219], v[84:87]
	v_mfma_f32_16x16x32_bf16 v[80:83], v[192:195], v[216:219], v[80:83]
	v_mfma_f32_16x16x32_bf16 v[68:71], v[184:187], v[224:227], v[68:71]
	v_mfma_f32_16x16x32_bf16 v[64:67], v[192:195], v[224:227], v[64:67]
	s_setprio 0
	s_barrier
; #define PG8_STAGE(bufoff, gbase, voff) do { _Pragma("unroll") for (int _i = 0; _i < 2; ++_i) \
;         __builtin_amdgcn_global_load_lds((const unsigned*)((const char*)(gbase) + (voff)[_i]), (PG8_LAS unsigned*)(lds + (bufoff) + ldsw + _i * 8192), 16, 0, 0); } while (0)
; #define PG8_LDA(dst, b, h) do { _Pragma("unroll") for (int m = 0; m < 4; ++m) _Pragma("unroll") for (int k = 0; k < 2; ++k) dst[m][k] = *(const PG8_LAS bf16x8*)(lds + PG8_SA(b, h) + aoff + m * 2048 + k * 1024); } while (0)
; #define PG8_MMA(ai, bj, At, Bt) do { __builtin_amdgcn_s_setprio(1); _Pragma("unroll") for (int m = 0; m < 4; ++m) _Pragma("unroll") for (int n = 0; n < 2; ++n) _Pragma("unroll") for (int k = 0; k < 2; ++k) \
;         acc[ai][bj][m][n] = __builtin_amdgcn_mfma_f32_16x16x32_bf16(Bt[n][k], At[m][k], acc[ai][bj][m][n], 0, 0, 0); __builtin_amdgcn_s_setprio(0); } while (0)
; #define PG8_WAIT_V(n) asm volatile("s_waitcnt vmcnt(" #n ")" ::: "memory")
; #define PG8_WAIT_L(n) asm volatile("s_waitcnt lgkmcnt(" #n ")" ::: "memory")
; #define PG8_BAR __builtin_amdgcn_s_barrier()
; #define PG8_SCHED __builtin_amdgcn_sched_barrier(0)
; template <class Epi, class Sched, bool ALIGN_EPI = false, bool SP2 = false, bool ABLK = false>
; __device__ __forceinline__ void gemm_phase(PG8_LAS unsigned char* lds, const Gemm g, const Sched& S, const Epi& E) {
;     ...
;             PG8_WAIT_V(8); PG8_WAIT_L(0); PG8_BAR; PG8_MMA(0, 0, At, B0); PG8_MMA(0, 1, At, B1); PG8_BAR; PG8_SCHED;
;             PG8_LDA(At, 1, 1); PG8_STAGE(PG8_SB(1, 0), b3, voffB); PG8_STAGE(PG8_SB(1, 1), b3 + hstep, voffB); PG8_STAGE(PG8_SA(1, 0), a3, voffA);
;             PG8_WAIT_V(8); PG8_WAIT_L(0); PG8_BAR; PG8_MMA(1, 0, At, B0); PG8_MMA(1, 1, At, B1); PG8_BAR; PG8_SCHED;
	s_add_i32 s28, s53, s30
	v_lshl_add_u64 v[156:157], v[156:157], 0, s[8:9]
	s_mov_b32 m0, s28
	ds_read_b128 v[196:199], v161 offset:49152
	ds_read_b128 v[200:203], v161 offset:50176
	ds_read_b128 v[204:207], v161 offset:51200
	ds_read_b128 v[208:211], v161 offset:52224
	ds_read_b128 v[212:215], v161 offset:53248
	ds_read_b128 v[216:219], v161 offset:54272
	ds_read_b128 v[220:223], v161 offset:55296
	ds_read_b128 v[224:227], v161 offset:56320
	global_load_lds_dwordx4 v[156:157], off
	s_add_i32 m0, s28, 0x2000
	s_add_u32 s26, s26, 0x40080
	v_lshl_add_u64 v[156:157], v[228:229], 0, s[8:9]
	s_addc_u32 s27, s27, 0
	s_add_i32 s28, s54, s30
	global_load_lds_dwordx4 v[156:157], off
	v_lshl_add_u64 v[156:157], s[26:27], 0, v[132:133]
	s_mov_b32 m0, s28
	s_nop 0
	global_load_lds_dwordx4 v[156:157], off
	v_lshl_add_u64 v[156:157], s[26:27], 0, v[128:129]
	s_add_i32 m0, s28, 0x2000
	s_nop 0
	global_load_lds_dwordx4 v[156:157], off
	v_lshl_add_u64 v[156:157], v[230:231], 0, s[8:9]
	s_mov_b32 m0, s41
	s_nop 0
	global_load_lds_dwordx4 v[156:157], off
	v_lshl_add_u64 v[156:157], v[232:233], 0, s[8:9]
	s_mov_b32 m0, s42
	s_nop 0
	global_load_lds_dwordx4 v[156:157], off
	s_waitcnt vmcnt(8)
	s_waitcnt lgkmcnt(0)
	s_barrier
	s_setprio 1
	s_waitcnt lgkmcnt(0)
	v_mfma_f32_16x16x32_bf16 v[60:63], v[162:165], v[196:199], v[60:63]
	v_mfma_f32_16x16x32_bf16 v[56:59], v[172:175], v[196:199], v[56:59]
	v_mfma_f32_16x16x32_bf16 v[44:47], v[162:165], v[204:207], v[44:47]
	v_mfma_f32_16x16x32_bf16 v[40:43], v[172:175], v[204:207], v[40:43]
	v_mfma_f32_16x16x32_bf16 v[28:31], v[162:165], v[212:215], v[28:31]
	v_mfma_f32_16x16x32_bf16 v[24:27], v[172:175], v[212:215], v[24:27]
	v_mfma_f32_16x16x32_bf16 v[12:15], v[162:165], v[220:223], v[12:15]
	v_mfma_f32_16x16x32_bf16 v[8:11], v[172:175], v[220:223], v[8:11]
	v_mfma_f32_16x16x32_bf16 v[60:63], v[168:171], v[200:203], v[60:63]
	v_mfma_f32_16x16x32_bf16 v[56:59], v[176:179], v[200:203], v[56:59]
	v_mfma_f32_16x16x32_bf16 v[44:47], v[168:171], v[208:211], v[44:47]
	v_mfma_f32_16x16x32_bf16 v[40:43], v[176:179], v[208:211], v[40:43]
	v_mfma_f32_16x16x32_bf16 v[28:31], v[168:171], v[216:219], v[28:31]
	v_mfma_f32_16x16x32_bf16 v[24:27], v[176:179], v[216:219], v[24:27]
	v_mfma_f32_16x16x32_bf16 v[12:15], v[168:171], v[224:227], v[12:15]
	v_mfma_f32_16x16x32_bf16 v[8:11], v[176:179], v[224:227], v[8:11]
	s_setprio 0
	s_setprio 1
	v_mfma_f32_16x16x32_bf16 v[52:55], v[180:183], v[196:199], v[52:55]
	v_mfma_f32_16x16x32_bf16 v[48:51], v[188:191], v[196:199], v[48:51]
	v_mfma_f32_16x16x32_bf16 v[36:39], v[180:183], v[204:207], v[36:39]
	v_mfma_f32_16x16x32_bf16 v[32:35], v[188:191], v[204:207], v[32:35]
	v_mfma_f32_16x16x32_bf16 v[20:23], v[180:183], v[212:215], v[20:23]
	v_mfma_f32_16x16x32_bf16 v[16:19], v[188:191], v[212:215], v[16:19]
	v_mfma_f32_16x16x32_bf16 v[4:7], v[180:183], v[220:223], v[4:7]
	v_mfma_f32_16x16x32_bf16 v[0:3], v[188:191], v[220:223], v[0:3]
	v_mfma_f32_16x16x32_bf16 v[52:55], v[184:187], v[200:203], v[52:55]
	v_mfma_f32_16x16x32_bf16 v[48:51], v[192:195], v[200:203], v[48:51]
	v_mfma_f32_16x16x32_bf16 v[36:39], v[184:187], v[208:211], v[36:39]
	v_mfma_f32_16x16x32_bf16 v[32:35], v[192:195], v[208:211], v[32:35]
	v_mfma_f32_16x16x32_bf16 v[20:23], v[184:187], v[216:219], v[20:23]
	v_mfma_f32_16x16x32_bf16 v[16:19], v[192:195], v[216:219], v[16:19]
	v_mfma_f32_16x16x32_bf16 v[4:7], v[184:187], v[224:227], v[4:7]
	v_mfma_f32_16x16x32_bf16 v[0:3], v[192:195], v[224:227], v[0:3]
	s_setprio 0
	s_barrier
	s_add_i32 s51, s51, 2
	s_add_u32 s24, s24, 0x100
	s_addc_u32 s25, s25, 0
	s_add_u32 s49, s49, 0x100
	s_addc_u32 s50, s50, 0
	s_cmp_gt_u32 s51, 13
	s_cbranch_scc1 .Lpeel_post_0

; #define PG8_BAR __builtin_amdgcn_s_barrier()
; template <class Epi, class Sched, bool ALIGN_EPI = false, bool SP2 = false, bool ABLK = false>
; __device__ __forceinline__ void gemm_phase(PG8_LAS unsigned char* lds, const Gemm g, const Sched& S, const Epi& E) {
;     ...
;         if constexpr (ALIGN_EPI) { if (wr == 0) PG8_BAR; }
.Lpeel_post_0:
	s_and_b64 vcc, exec, s[10:11]
	s_cbranch_vccz .LBB0_178
	s_barrier

; #define PG8_STAGE(bufoff, gbase, voff) do { _Pragma("unroll") for (int _i = 0; _i < 2; ++_i) \
;         __builtin_amdgcn_global_load_lds((const unsigned*)((const char*)(gbase) + (voff)[_i]), (PG8_LAS unsigned*)(lds + (bufoff) + ldsw + _i * 8192), 16, 0, 0); } while (0)
; #define PG8_LDA(dst, b, h) do { _Pragma("unroll") for (int m = 0; m < 4; ++m) _Pragma("unroll") for (int k = 0; k < 2; ++k) dst[m][k] = *(const PG8_LAS bf16x8*)(lds + PG8_SA(b, h) + aoff + m * 2048 + k * 1024); } while (0)
; #define PG8_LDB(dst, b, h) do { _Pragma("unroll") for (int n = 0; n < 2; ++n) _Pragma("unroll") for (int k = 0; k < 2; ++k) dst[n][k] = *(const PG8_LAS bf16x8*)(lds + PG8_SB(b, h) + boff + n * 2048 + k * 1024); } while (0)
; #define PG8_MMA(ai, bj, At, Bt) do { __builtin_amdgcn_s_setprio(1); _Pragma("unroll") for (int m = 0; m < 4; ++m) _Pragma("unroll") for (int n = 0; n < 2; ++n) _Pragma("unroll") for (int k = 0; k < 2; ++k) \
;         acc[ai][bj][m][n] = __builtin_amdgcn_mfma_f32_16x16x32_bf16(Bt[n][k], At[m][k], acc[ai][bj][m][n], 0, 0, 0); __builtin_amdgcn_s_setprio(0); } while (0)
; #define PG8_WAIT_V(n) asm volatile("s_waitcnt vmcnt(" #n ")" ::: "memory")
; #define PG8_WAIT_L(n) asm volatile("s_waitcnt lgkmcnt(" #n ")" ::: "memory")
; #define PG8_BAR __builtin_amdgcn_s_barrier()
; #define PG8_SCHED __builtin_amdgcn_sched_barrier(0)
; template <class Epi, class Sched, bool ALIGN_EPI = false, bool SP2 = false, bool ABLK = false>
; __device__ __forceinline__ void gemm_phase(PG8_LAS unsigned char* lds, const Gemm g, const Sched& S, const Epi& E) {
;     ...
;             PG8_LDB(B0, 0, 0); PG8_LDB(B1, 0, 1); PG8_SCHED; PG8_LDA(At, 0, 0); PG8_STAGE(PG8_SA(1, 1), a1 + hstepA, voffA);
;             PG8_WAIT_V(8); PG8_WAIT_L(0); PG8_BAR; PG8_MMA(0, 0, At, B0); PG8_MMA(0, 1, At, B1); PG8_BAR; PG8_SCHED;
;             PG8_LDA(At, 0, 1); PG8_STAGE(PG8_SB(0, 0), b2, voffB); PG8_STAGE(PG8_SB(0, 1), b2 + hstep, voffB); PG8_STAGE(PG8_SA(0, 0), a2, voffA);
;             PG8_WAIT_V(8); PG8_WAIT_L(0); PG8_BAR; PG8_MMA(1, 0, At, B0); PG8_MMA(1, 1, At, B1); PG8_BAR; PG8_SCHED;
;     ...
; #pragma unroll
;         for (int a = 0; a < 2; ++a)
; #pragma unroll
;             for (int b = 0; b < 2; ++b)
; #pragma unroll
;                 for (int m = 0; m < 4; ++m)
; #pragma unroll
;                     for (int n = 0; n < 2; ++n) acc[a][b][m][n] = (f32x4){0.f, 0.f, 0.f, 0.f};
.LBB0_256:
	ds_read_b128 v[144:147], v151
	ds_read_b128 v[156:159], v151 offset:1024
	ds_read_b128 v[160:163], v151 offset:2048
	ds_read_b128 v[168:171], v151 offset:3072
	ds_read_b128 v[172:175], v152
	ds_read_b128 v[176:179], v152 offset:1024
	ds_read_b128 v[180:183], v152 offset:2048
	ds_read_b128 v[184:187], v152 offset:3072
	s_add_u32 s16, s44, 0x4000
	s_addc_u32 s17, s45, 0
	s_cmp_eq_u32 s68, 40
	s_cselect_b32 s52, s0, s16
	s_cselect_b32 s53, s1, s17
	s_cselect_b32 s50, s36, s14
	s_cselect_b32 s51, s37, s15
	s_add_u32 s46, s52, 0x8000
	s_addc_u32 s47, s53, 0
	v_lshl_add_u64 v[164:165], s[44:45], 0, v[136:137]
	s_add_i32 m0, s7, 0xc000
	ds_read_b128 v[188:191], v153
	ds_read_b128 v[192:195], v153 offset:1024
	ds_read_b128 v[196:199], v153 offset:2048
	ds_read_b128 v[200:203], v153 offset:3072
	ds_read_b128 v[204:207], v153 offset:4096
	ds_read_b128 v[208:211], v153 offset:5120
	ds_read_b128 v[212:215], v153 offset:6144
	ds_read_b128 v[216:219], v153 offset:7168
	global_load_lds_dwordx4 v[164:165], off
	v_lshl_add_u64 v[164:165], s[44:45], 0, v[138:139]
	s_add_i32 m0, s7, 0xe000
	s_nop 0
	global_load_lds_dwordx4 v[164:165], off
	s_waitcnt vmcnt(8)
	s_waitcnt lgkmcnt(0)
	s_barrier
	s_setprio 1
	s_waitcnt lgkmcnt(0)
	v_mfma_f32_16x16x32_bf16 v[124:127], v[144:147], v[188:191], 0
	v_mfma_f32_16x16x32_bf16 v[120:123], v[160:163], v[188:191], 0
	v_mfma_f32_16x16x32_bf16 v[108:111], v[144:147], v[196:199], 0
	v_mfma_f32_16x16x32_bf16 v[104:107], v[160:163], v[196:199], 0
	v_mfma_f32_16x16x32_bf16 v[92:95], v[144:147], v[204:207], 0
	v_mfma_f32_16x16x32_bf16 v[88:91], v[160:163], v[204:207], 0
	v_mfma_f32_16x16x32_bf16 v[76:79], v[144:147], v[212:215], 0
	v_mfma_f32_16x16x32_bf16 v[72:75], v[160:163], v[212:215], 0
	v_mfma_f32_16x16x32_bf16 v[124:127], v[156:159], v[192:195], v[124:127]
	v_mfma_f32_16x16x32_bf16 v[120:123], v[168:171], v[192:195], v[120:123]
	v_mfma_f32_16x16x32_bf16 v[108:111], v[156:159], v[200:203], v[108:111]
	v_mfma_f32_16x16x32_bf16 v[104:107], v[168:171], v[200:203], v[104:107]
	v_mfma_f32_16x16x32_bf16 v[92:95], v[156:159], v[208:211], v[92:95]
	v_mfma_f32_16x16x32_bf16 v[88:91], v[168:171], v[208:211], v[88:91]
	v_mfma_f32_16x16x32_bf16 v[76:79], v[156:159], v[216:219], v[76:79]
	v_mfma_f32_16x16x32_bf16 v[72:75], v[168:171], v[216:219], v[72:75]
	s_setprio 0
	s_setprio 1
	v_mfma_f32_16x16x32_bf16 v[116:119], v[172:175], v[188:191], 0
	v_mfma_f32_16x16x32_bf16 v[112:115], v[180:183], v[188:191], 0
	v_mfma_f32_16x16x32_bf16 v[100:103], v[172:175], v[196:199], 0
	v_mfma_f32_16x16x32_bf16 v[96:99], v[180:183], v[196:199], 0
	v_mfma_f32_16x16x32_bf16 v[84:87], v[172:175], v[204:207], 0
	v_mfma_f32_16x16x32_bf16 v[80:83], v[180:183], v[204:207], 0
	v_mfma_f32_16x16x32_bf16 v[68:71], v[172:175], v[212:215], 0
	v_mfma_f32_16x16x32_bf16 v[64:67], v[180:183], v[212:215], 0
	v_mfma_f32_16x16x32_bf16 v[116:119], v[176:179], v[192:195], v[116:119]
	v_mfma_f32_16x16x32_bf16 v[112:115], v[184:187], v[192:195], v[112:115]
	v_mfma_f32_16x16x32_bf16 v[100:103], v[176:179], v[200:203], v[100:103]
	v_mfma_f32_16x16x32_bf16 v[96:99], v[184:187], v[200:203], v[96:99]
	v_mfma_f32_16x16x32_bf16 v[84:87], v[176:179], v[208:211], v[84:87]
	v_mfma_f32_16x16x32_bf16 v[80:83], v[184:187], v[208:211], v[80:83]
	v_mfma_f32_16x16x32_bf16 v[68:71], v[176:179], v[216:219], v[68:71]
	v_mfma_f32_16x16x32_bf16 v[64:67], v[184:187], v[216:219], v[64:67]
	s_setprio 0
	s_barrier
	s_add_i32 s16, s58, s4
	v_lshl_add_u64 v[164:165], s[50:51], 0, v[130:131]
	s_mov_b32 m0, s16
	ds_read_b128 v[188:191], v153 offset:16384
	ds_read_b128 v[192:195], v153 offset:17408
	ds_read_b128 v[196:199], v153 offset:18432
	ds_read_b128 v[200:203], v153 offset:19456
	ds_read_b128 v[204:207], v153 offset:20480
	ds_read_b128 v[208:211], v153 offset:21504
	ds_read_b128 v[212:215], v153 offset:22528
	ds_read_b128 v[216:219], v153 offset:23552
	global_load_lds_dwordx4 v[164:165], off
	s_add_i32 m0, s16, 0x2000
	s_add_u32 s16, s50, 0xb0000
	v_lshl_add_u64 v[220:221], s[50:51], 0, v[134:135]
	s_addc_u32 s17, s51, 0
	s_add_i32 s18, s59, s4
	global_load_lds_dwordx4 v[220:221], off
	v_lshl_add_u64 v[222:223], s[16:17], 0, v[130:131]
	s_mov_b32 m0, s18
	s_nop 0
	global_load_lds_dwordx4 v[222:223], off
	v_lshl_add_u64 v[222:223], s[16:17], 0, v[134:135]
	s_add_i32 m0, s18, 0x2000
	s_nop 0
	global_load_lds_dwordx4 v[222:223], off
	v_lshl_add_u64 v[222:223], s[52:53], 0, v[128:129]
	s_mov_b32 m0, s7
	s_nop 0
	global_load_lds_dwordx4 v[222:223], off
	v_lshl_add_u64 v[222:223], s[52:53], 0, v[132:133]
	s_mov_b32 m0, s54
	s_nop 0
	global_load_lds_dwordx4 v[222:223], off
	s_waitcnt vmcnt(8)
	s_waitcnt lgkmcnt(0)
	s_barrier
; #define PG8_STAGE(bufoff, gbase, voff) do { _Pragma("unroll") for (int _i = 0; _i < 2; ++_i) \
;         __builtin_amdgcn_global_load_lds((const unsigned*)((const char*)(gbase) + (voff)[_i]), (PG8_LAS unsigned*)(lds + (bufoff) + ldsw + _i * 8192), 16, 0, 0); } while (0)
; #define PG8_LDA(dst, b, h) do { _Pragma("unroll") for (int m = 0; m < 4; ++m) _Pragma("unroll") for (int k = 0; k < 2; ++k) dst[m][k] = *(const PG8_LAS bf16x8*)(lds + PG8_SA(b, h) + aoff + m * 2048 + k * 1024); } while (0)
; #define PG8_LDB(dst, b, h) do { _Pragma("unroll") for (int n = 0; n < 2; ++n) _Pragma("unroll") for (int k = 0; k < 2; ++k) dst[n][k] = *(const PG8_LAS bf16x8*)(lds + PG8_SB(b, h) + boff + n * 2048 + k * 1024); } while (0)
; #define PG8_MMA(ai, bj, At, Bt) do { __builtin_amdgcn_s_setprio(1); _Pragma("unroll") for (int m = 0; m < 4; ++m) _Pragma("unroll") for (int n = 0; n < 2; ++n) _Pragma("unroll") for (int k = 0; k < 2; ++k) \
;         acc[ai][bj][m][n] = __builtin_amdgcn_mfma_f32_16x16x32_bf16(Bt[n][k], At[m][k], acc[ai][bj][m][n], 0, 0, 0); __builtin_amdgcn_s_setprio(0); } while (0)
; #define PG8_WAIT_V(n) asm volatile("s_waitcnt vmcnt(" #n ")" ::: "memory")
; #define PG8_WAIT_L(n) asm volatile("s_waitcnt lgkmcnt(" #n ")" ::: "memory")
; #define PG8_BAR __builtin_amdgcn_s_barrier()
; #define PG8_SCHED __builtin_amdgcn_sched_barrier(0)
; template <class Epi, class Sched, bool ALIGN_EPI = false, bool SP2 = false, bool ABLK = false>
; __device__ __forceinline__ void gemm_phase(PG8_LAS unsigned char* lds, const Gemm g, const Sched& S, const Epi& E) {
;     ...
;             PG8_WAIT_V(8); PG8_WAIT_L(0); PG8_BAR; PG8_MMA(1, 0, At, B0); PG8_MMA(1, 1, At, B1); PG8_BAR; PG8_SCHED;
;             PG8_LDB(B0, 1, 0); PG8_LDB(B1, 1, 1); PG8_SCHED; PG8_LDA(At, 1, 0); PG8_STAGE(PG8_SA(0, 1), a2 + hstepA, voffA);
;             PG8_WAIT_V(8); PG8_WAIT_L(0); PG8_BAR; PG8_MMA(0, 0, At, B0); PG8_MMA(0, 1, At, B1); PG8_BAR; PG8_SCHED;
	s_setprio 1
	s_waitcnt lgkmcnt(0)
	v_mfma_f32_16x16x32_bf16 v[60:63], v[144:147], v[188:191], 0
	v_mfma_f32_16x16x32_bf16 v[56:59], v[160:163], v[188:191], 0
	v_mfma_f32_16x16x32_bf16 v[44:47], v[144:147], v[196:199], 0
	v_mfma_f32_16x16x32_bf16 v[40:43], v[160:163], v[196:199], 0
	v_mfma_f32_16x16x32_bf16 v[28:31], v[144:147], v[204:207], 0
	v_mfma_f32_16x16x32_bf16 v[24:27], v[160:163], v[204:207], 0
	v_mfma_f32_16x16x32_bf16 v[12:15], v[144:147], v[212:215], 0
	v_mfma_f32_16x16x32_bf16 v[8:11], v[160:163], v[212:215], 0
	v_mfma_f32_16x16x32_bf16 v[60:63], v[156:159], v[192:195], v[60:63]
	v_mfma_f32_16x16x32_bf16 v[56:59], v[168:171], v[192:195], v[56:59]
	v_mfma_f32_16x16x32_bf16 v[44:47], v[156:159], v[200:203], v[44:47]
	v_mfma_f32_16x16x32_bf16 v[40:43], v[168:171], v[200:203], v[40:43]
	v_mfma_f32_16x16x32_bf16 v[28:31], v[156:159], v[208:211], v[28:31]
	v_mfma_f32_16x16x32_bf16 v[24:27], v[168:171], v[208:211], v[24:27]
	v_mfma_f32_16x16x32_bf16 v[12:15], v[156:159], v[216:219], v[12:15]
	v_mfma_f32_16x16x32_bf16 v[8:11], v[168:171], v[216:219], v[8:11]
	s_setprio 0
	s_setprio 1
	v_mfma_f32_16x16x32_bf16 v[52:55], v[172:175], v[188:191], 0
	v_mfma_f32_16x16x32_bf16 v[48:51], v[180:183], v[188:191], 0
	v_mfma_f32_16x16x32_bf16 v[36:39], v[172:175], v[196:199], 0
	v_mfma_f32_16x16x32_bf16 v[32:35], v[180:183], v[196:199], 0
	v_mfma_f32_16x16x32_bf16 v[20:23], v[172:175], v[204:207], 0
	v_mfma_f32_16x16x32_bf16 v[16:19], v[180:183], v[204:207], 0
	v_mfma_f32_16x16x32_bf16 v[4:7], v[172:175], v[212:215], 0
	v_mfma_f32_16x16x32_bf16 v[0:3], v[180:183], v[212:215], 0
	v_mfma_f32_16x16x32_bf16 v[52:55], v[176:179], v[192:195], v[52:55]
	v_mfma_f32_16x16x32_bf16 v[48:51], v[184:187], v[192:195], v[48:51]
	v_mfma_f32_16x16x32_bf16 v[36:39], v[176:179], v[200:203], v[36:39]
	v_mfma_f32_16x16x32_bf16 v[32:35], v[184:187], v[200:203], v[32:35]
	v_mfma_f32_16x16x32_bf16 v[20:23], v[176:179], v[208:211], v[20:23]
	v_mfma_f32_16x16x32_bf16 v[16:19], v[184:187], v[208:211], v[16:19]
	v_mfma_f32_16x16x32_bf16 v[4:7], v[176:179], v[216:219], v[4:7]
	v_mfma_f32_16x16x32_bf16 v[0:3], v[184:187], v[216:219], v[0:3]
	s_setprio 0
	s_barrier
	s_add_i32 s18, 0, 0x18000
	v_add_u32_e32 v155, s18, v149
	s_add_i32 s19, 0, 0x1c000
	ds_read_b128 v[144:147], v155
	ds_read_b128 v[156:159], v155 offset:1024
	ds_read_b128 v[160:163], v155 offset:2048
	ds_read_b128 v[168:171], v155 offset:3072
	v_add_u32_e32 v155, s19, v149
	ds_read_b128 v[172:175], v155
	ds_read_b128 v[176:179], v155 offset:1024
	ds_read_b128 v[180:183], v155 offset:2048
	ds_read_b128 v[184:187], v155 offset:3072
	s_add_u32 s16, s52, 0x4000
	s_addc_u32 s17, s53, 0
	s_mov_b32 m0, s8
	v_lshl_add_u64 v[222:223], s[16:17], 0, v[128:129]
	ds_read_b128 v[188:191], v153 offset:32768
	ds_read_b128 v[192:195], v153 offset:33792
	ds_read_b128 v[196:199], v153 offset:34816
	ds_read_b128 v[200:203], v153 offset:35840
	ds_read_b128 v[204:207], v153 offset:36864
	ds_read_b128 v[208:211], v153 offset:37888
	ds_read_b128 v[212:215], v153 offset:38912
	ds_read_b128 v[216:219], v153 offset:39936
	global_load_lds_dwordx4 v[222:223], off
	v_lshl_add_u64 v[222:223], s[16:17], 0, v[132:133]
	s_mov_b32 m0, s9
	s_nop 0
	global_load_lds_dwordx4 v[222:223], off
	s_waitcnt vmcnt(8)
	s_waitcnt lgkmcnt(0)
	s_barrier
	s_setprio 1
	s_waitcnt lgkmcnt(0)
	v_mfma_f32_16x16x32_bf16 v[124:127], v[144:147], v[188:191], v[124:127]
	v_mfma_f32_16x16x32_bf16 v[120:123], v[160:163], v[188:191], v[120:123]
	v_mfma_f32_16x16x32_bf16 v[108:111], v[144:147], v[196:199], v[108:111]
	v_mfma_f32_16x16x32_bf16 v[104:107], v[160:163], v[196:199], v[104:107]
	v_mfma_f32_16x16x32_bf16 v[92:95], v[144:147], v[204:207], v[92:95]
	v_mfma_f32_16x16x32_bf16 v[88:91], v[160:163], v[204:207], v[88:91]
	v_mfma_f32_16x16x32_bf16 v[76:79], v[144:147], v[212:215], v[76:79]
	v_mfma_f32_16x16x32_bf16 v[72:75], v[160:163], v[212:215], v[72:75]
	v_mfma_f32_16x16x32_bf16 v[124:127], v[156:159], v[192:195], v[124:127]
	v_mfma_f32_16x16x32_bf16 v[120:123], v[168:171], v[192:195], v[120:123]
	v_mfma_f32_16x16x32_bf16 v[108:111], v[156:159], v[200:203], v[108:111]
	v_mfma_f32_16x16x32_bf16 v[104:107], v[168:171], v[200:203], v[104:107]
	v_mfma_f32_16x16x32_bf16 v[92:95], v[156:159], v[208:211], v[92:95]
	v_mfma_f32_16x16x32_bf16 v[88:91], v[168:171], v[208:211], v[88:91]
	v_mfma_f32_16x16x32_bf16 v[76:79], v[156:159], v[216:219], v[76:79]
	v_mfma_f32_16x16x32_bf16 v[72:75], v[168:171], v[216:219], v[72:75]
	s_setprio 0
	s_setprio 1
	v_mfma_f32_16x16x32_bf16 v[116:119], v[172:175], v[188:191], v[116:119]
	v_mfma_f32_16x16x32_bf16 v[112:115], v[180:183], v[188:191], v[112:115]
	v_mfma_f32_16x16x32_bf16 v[100:103], v[172:175], v[196:199], v[100:103]
	v_mfma_f32_16x16x32_bf16 v[96:99], v[180:183], v[196:199], v[96:99]
	v_mfma_f32_16x16x32_bf16 v[84:87], v[172:175], v[204:207], v[84:87]
	v_mfma_f32_16x16x32_bf16 v[80:83], v[180:183], v[204:207], v[80:83]
	v_mfma_f32_16x16x32_bf16 v[68:71], v[172:175], v[212:215], v[68:71]
	v_mfma_f32_16x16x32_bf16 v[64:67], v[180:183], v[212:215], v[64:67]
	v_mfma_f32_16x16x32_bf16 v[116:119], v[176:179], v[192:195], v[116:119]
	v_mfma_f32_16x16x32_bf16 v[112:115], v[184:187], v[192:195], v[112:115]
	v_mfma_f32_16x16x32_bf16 v[100:103], v[176:179], v[200:203], v[100:103]
	v_mfma_f32_16x16x32_bf16 v[96:99], v[184:187], v[200:203], v[96:99]
	v_mfma_f32_16x16x32_bf16 v[84:87], v[176:179], v[208:211], v[84:87]
	v_mfma_f32_16x16x32_bf16 v[80:83], v[184:187], v[208:211], v[80:83]
	v_mfma_f32_16x16x32_bf16 v[68:71], v[176:179], v[216:219], v[68:71]
	v_mfma_f32_16x16x32_bf16 v[64:67], v[184:187], v[216:219], v[64:67]
	s_setprio 0
	s_barrier
; #define PG8_STAGE(bufoff, gbase, voff) do { _Pragma("unroll") for (int _i = 0; _i < 2; ++_i) \
;         __builtin_amdgcn_global_load_lds((const unsigned*)((const char*)(gbase) + (voff)[_i]), (PG8_LAS unsigned*)(lds + (bufoff) + ldsw + _i * 8192), 16, 0, 0); } while (0)
; #define PG8_LDA(dst, b, h) do { _Pragma("unroll") for (int m = 0; m < 4; ++m) _Pragma("unroll") for (int k = 0; k < 2; ++k) dst[m][k] = *(const PG8_LAS bf16x8*)(lds + PG8_SA(b, h) + aoff + m * 2048 + k * 1024); } while (0)
; #define PG8_MMA(ai, bj, At, Bt) do { __builtin_amdgcn_s_setprio(1); _Pragma("unroll") for (int m = 0; m < 4; ++m) _Pragma("unroll") for (int n = 0; n < 2; ++n) _Pragma("unroll") for (int k = 0; k < 2; ++k) \
;         acc[ai][bj][m][n] = __builtin_amdgcn_mfma_f32_16x16x32_bf16(Bt[n][k], At[m][k], acc[ai][bj][m][n], 0, 0, 0); __builtin_amdgcn_s_setprio(0); } while (0)
; #define PG8_WAIT_V(n) asm volatile("s_waitcnt vmcnt(" #n ")" ::: "memory")
; #define PG8_WAIT_L(n) asm volatile("s_waitcnt lgkmcnt(" #n ")" ::: "memory")
; #define PG8_BAR __builtin_amdgcn_s_barrier()
; #define PG8_SCHED __builtin_amdgcn_sched_barrier(0)
; template <class Epi, class Sched, bool ALIGN_EPI = false, bool SP2 = false, bool ABLK = false>
; __device__ __forceinline__ void gemm_phase(PG8_LAS unsigned char* lds, const Gemm g, const Sched& S, const Epi& E) {
;     ...
;             PG8_WAIT_V(8); PG8_WAIT_L(0); PG8_BAR; PG8_MMA(0, 0, At, B0); PG8_MMA(0, 1, At, B1); PG8_BAR; PG8_SCHED;
;             PG8_LDA(At, 1, 1); PG8_STAGE(PG8_SB(1, 0), b3, voffB); PG8_STAGE(PG8_SB(1, 1), b3 + hstep, voffB); PG8_STAGE(PG8_SA(1, 0), a3, voffA);
;             PG8_WAIT_V(8); PG8_WAIT_L(0); PG8_BAR; PG8_MMA(1, 0, At, B0); PG8_MMA(1, 1, At, B1); PG8_BAR; PG8_SCHED;
	s_add_i32 s16, s18, s4
	v_lshl_add_u64 v[164:165], v[164:165], 0, s[30:31]
	s_mov_b32 m0, s16
	ds_read_b128 v[188:191], v153 offset:49152
	ds_read_b128 v[192:195], v153 offset:50176
	ds_read_b128 v[196:199], v153 offset:51200
	ds_read_b128 v[200:203], v153 offset:52224
	ds_read_b128 v[204:207], v153 offset:53248
	ds_read_b128 v[208:211], v153 offset:54272
	ds_read_b128 v[212:215], v153 offset:55296
	ds_read_b128 v[216:219], v153 offset:56320
	global_load_lds_dwordx4 v[164:165], off
	s_add_i32 m0, s16, 0x2000
	s_add_u32 s16, s50, 0xb0080
	v_lshl_add_u64 v[164:165], v[220:221], 0, s[30:31]
	s_addc_u32 s17, s51, 0
	s_add_i32 s18, s19, s4
	global_load_lds_dwordx4 v[164:165], off
	v_lshl_add_u64 v[164:165], s[16:17], 0, v[130:131]
	s_mov_b32 m0, s18
	s_nop 0
	global_load_lds_dwordx4 v[164:165], off
	v_lshl_add_u64 v[164:165], s[16:17], 0, v[134:135]
	s_add_i32 m0, s18, 0x2000
	s_nop 0
	global_load_lds_dwordx4 v[164:165], off
	v_lshl_add_u64 v[164:165], s[46:47], 0, v[128:129]
	s_mov_b32 m0, s11
	s_nop 0
	global_load_lds_dwordx4 v[164:165], off
	v_lshl_add_u64 v[164:165], s[46:47], 0, v[132:133]
	s_mov_b32 m0, s55
	s_nop 0
	global_load_lds_dwordx4 v[164:165], off
	s_waitcnt vmcnt(8)
	s_waitcnt lgkmcnt(0)
	s_barrier
	s_setprio 1
	s_waitcnt lgkmcnt(0)
	v_mfma_f32_16x16x32_bf16 v[60:63], v[144:147], v[188:191], v[60:63]
	v_mfma_f32_16x16x32_bf16 v[56:59], v[160:163], v[188:191], v[56:59]
	v_mfma_f32_16x16x32_bf16 v[44:47], v[144:147], v[196:199], v[44:47]
	v_mfma_f32_16x16x32_bf16 v[40:43], v[160:163], v[196:199], v[40:43]
	v_mfma_f32_16x16x32_bf16 v[28:31], v[144:147], v[204:207], v[28:31]
	v_mfma_f32_16x16x32_bf16 v[24:27], v[160:163], v[204:207], v[24:27]
	v_mfma_f32_16x16x32_bf16 v[12:15], v[144:147], v[212:215], v[12:15]
	v_mfma_f32_16x16x32_bf16 v[8:11], v[160:163], v[212:215], v[8:11]
	v_mfma_f32_16x16x32_bf16 v[60:63], v[156:159], v[192:195], v[60:63]
	v_mfma_f32_16x16x32_bf16 v[56:59], v[168:171], v[192:195], v[56:59]
	v_mfma_f32_16x16x32_bf16 v[44:47], v[156:159], v[200:203], v[44:47]
	v_mfma_f32_16x16x32_bf16 v[40:43], v[168:171], v[200:203], v[40:43]
	v_mfma_f32_16x16x32_bf16 v[28:31], v[156:159], v[208:211], v[28:31]
	v_mfma_f32_16x16x32_bf16 v[24:27], v[168:171], v[208:211], v[24:27]
	v_mfma_f32_16x16x32_bf16 v[12:15], v[156:159], v[216:219], v[12:15]
	v_mfma_f32_16x16x32_bf16 v[8:11], v[168:171], v[216:219], v[8:11]
	s_setprio 0
	s_setprio 1
	v_mfma_f32_16x16x32_bf16 v[52:55], v[172:175], v[188:191], v[52:55]
	v_mfma_f32_16x16x32_bf16 v[48:51], v[180:183], v[188:191], v[48:51]
	v_mfma_f32_16x16x32_bf16 v[36:39], v[172:175], v[196:199], v[36:39]
	v_mfma_f32_16x16x32_bf16 v[32:35], v[180:183], v[196:199], v[32:35]
	v_mfma_f32_16x16x32_bf16 v[20:23], v[172:175], v[204:207], v[20:23]
	v_mfma_f32_16x16x32_bf16 v[16:19], v[180:183], v[204:207], v[16:19]
	v_mfma_f32_16x16x32_bf16 v[4:7], v[172:175], v[212:215], v[4:7]
	v_mfma_f32_16x16x32_bf16 v[0:3], v[180:183], v[212:215], v[0:3]
	v_mfma_f32_16x16x32_bf16 v[52:55], v[176:179], v[192:195], v[52:55]
	v_mfma_f32_16x16x32_bf16 v[48:51], v[184:187], v[192:195], v[48:51]
	v_mfma_f32_16x16x32_bf16 v[36:39], v[176:179], v[200:203], v[36:39]
	v_mfma_f32_16x16x32_bf16 v[32:35], v[184:187], v[200:203], v[32:35]
	v_mfma_f32_16x16x32_bf16 v[20:23], v[176:179], v[208:211], v[20:23]
	v_mfma_f32_16x16x32_bf16 v[16:19], v[184:187], v[208:211], v[16:19]
	v_mfma_f32_16x16x32_bf16 v[4:7], v[176:179], v[216:219], v[4:7]
	v_mfma_f32_16x16x32_bf16 v[0:3], v[184:187], v[216:219], v[0:3]
	s_setprio 0
	s_barrier
	s_add_i32 s68, s68, 2
	s_add_u32 s14, s14, 0x100
	s_addc_u32 s15, s15, 0
	s_add_u32 s44, s44, 0x10000
	s_addc_u32 s45, s45, 0
	s_cmp_gt_u32 s68, 41
	s_cbranch_scc1 .Lpeel_post_1

; #define PG8_BAR __builtin_amdgcn_s_barrier()
; template <class Epi, class Sched, bool ALIGN_EPI = false, bool SP2 = false, bool ABLK = false>
; __device__ __forceinline__ void gemm_phase(PG8_LAS unsigned char* lds, const Gemm g, const Sched& S, const Epi& E) {
;     ...
;         if constexpr (ALIGN_EPI) { if (wr == 0) PG8_BAR; }
.Lpeel_post_1:
	s_and_b64 vcc, exec, s[34:35]
	s_cbranch_vccz .LBB0_259
	s_barrier

; #define PG8_STAGE(bufoff, gbase, voff) do { _Pragma("unroll") for (int _i = 0; _i < 2; ++_i) \
;         __builtin_amdgcn_global_load_lds((const unsigned*)((const char*)(gbase) + (voff)[_i]), (PG8_LAS unsigned*)(lds + (bufoff) + ldsw + _i * 8192), 16, 0, 0); } while (0)
; #define PG8_LDA(dst, b, h) do { _Pragma("unroll") for (int m = 0; m < 4; ++m) _Pragma("unroll") for (int k = 0; k < 2; ++k) dst[m][k] = *(const PG8_LAS bf16x8*)(lds + PG8_SA(b, h) + aoff + m * 2048 + k * 1024); } while (0)
; #define PG8_LDB(dst, b, h) do { _Pragma("unroll") for (int n = 0; n < 2; ++n) _Pragma("unroll") for (int k = 0; k < 2; ++k) dst[n][k] = *(const PG8_LAS bf16x8*)(lds + PG8_SB(b, h) + boff + n * 2048 + k * 1024); } while (0)
; #define PG8_MMA(ai, bj, At, Bt) do { __builtin_amdgcn_s_setprio(1); _Pragma("unroll") for (int m = 0; m < 4; ++m) _Pragma("unroll") for (int n = 0; n < 2; ++n) _Pragma("unroll") for (int k = 0; k < 2; ++k) \
;         acc[ai][bj][m][n] = __builtin_amdgcn_mfma_f32_16x16x32_bf16(Bt[n][k], At[m][k], acc[ai][bj][m][n], 0, 0, 0); __builtin_amdgcn_s_setprio(0); } while (0)
; #define PG8_WAIT_V(n) asm volatile("s_waitcnt vmcnt(" #n ")" ::: "memory")
; #define PG8_WAIT_L(n) asm volatile("s_waitcnt lgkmcnt(" #n ")" ::: "memory")
; #define PG8_BAR __builtin_amdgcn_s_barrier()
; #define PG8_SCHED __builtin_amdgcn_sched_barrier(0)
; template <class Epi, class Sched, bool ALIGN_EPI = false, bool SP2 = false, bool ABLK = false>
; __device__ __forceinline__ void gemm_phase(PG8_LAS unsigned char* lds, const Gemm g, const Sched& S, const Epi& E) {
;     ...
;             PG8_LDB(B0, 0, 0); PG8_LDB(B1, 0, 1); PG8_SCHED; PG8_LDA(At, 0, 0); PG8_STAGE(PG8_SA(1, 1), a1 + hstepA, voffA);
;             PG8_WAIT_V(8); PG8_WAIT_L(0); PG8_BAR; PG8_MMA(0, 0, At, B0); PG8_MMA(0, 1, At, B1); PG8_BAR; PG8_SCHED;
;             PG8_LDA(At, 0, 1); PG8_STAGE(PG8_SB(0, 0), b2, voffB); PG8_STAGE(PG8_SB(0, 1), b2 + hstep, voffB); PG8_STAGE(PG8_SA(0, 0), a2, voffA);
;             PG8_WAIT_V(8); PG8_WAIT_L(0); PG8_BAR; PG8_MMA(1, 0, At, B0); PG8_MMA(1, 1, At, B1); PG8_BAR; PG8_SCHED;
;     ...
; #pragma unroll
;         for (int a = 0; a < 2; ++a)
; #pragma unroll
;             for (int b = 0; b < 2; ++b)
; #pragma unroll
;                 for (int m = 0; m < 4; ++m)
; #pragma unroll
;                     for (int n = 0; n < 2; ++n) acc[a][b][m][n] = (f32x4){0.f, 0.f, 0.f, 0.f};
.LBB0_345:
	s_waitcnt lgkmcnt(0)
	ds_read_b128 v[152:155], v169
	ds_read_b128 v[156:159], v169 offset:1024
	ds_read_b128 v[160:163], v169 offset:2048
	ds_read_b128 v[176:179], v169 offset:3072
	ds_read_b128 v[180:183], v170
	ds_read_b128 v[184:187], v170 offset:1024
	ds_read_b128 v[188:191], v170 offset:2048
	ds_read_b128 v[192:195], v170 offset:3072
	s_add_u32 s10, s42, 0xfffc0080
	s_addc_u32 s11, s43, -1
	s_cmp_eq_u32 s9, 12
	s_cselect_b32 s67, s1, s11
	s_cselect_b32 s66, s4, s10
	s_cselect_b32 s53, s5, s8
	s_cselect_b32 s52, s6, s7
	v_lshl_add_u64 v[164:165], s[42:43], 0, v[144:145]
	s_add_i32 m0, s59, 0xc000
	ds_read_b128 v[196:199], v171
	ds_read_b128 v[200:203], v171 offset:1024
	ds_read_b128 v[204:207], v171 offset:2048
	ds_read_b128 v[208:211], v171 offset:3072
	ds_read_b128 v[212:215], v171 offset:4096
	ds_read_b128 v[216:219], v171 offset:5120
	ds_read_b128 v[220:223], v171 offset:6144
	ds_read_b128 v[224:227], v171 offset:7168
	global_load_lds_dwordx4 v[164:165], off
	v_lshl_add_u64 v[164:165], s[42:43], 0, v[146:147]
	s_add_i32 m0, s59, 0xe000
	s_nop 0
	global_load_lds_dwordx4 v[164:165], off
	s_waitcnt vmcnt(8)
	s_waitcnt lgkmcnt(0)
	s_barrier
	s_setprio 1
	s_waitcnt lgkmcnt(0)
	v_mfma_f32_16x16x32_bf16 v[124:127], v[152:155], v[196:199], 0
	v_mfma_f32_16x16x32_bf16 v[120:123], v[160:163], v[196:199], 0
	v_mfma_f32_16x16x32_bf16 v[108:111], v[152:155], v[204:207], 0
	v_mfma_f32_16x16x32_bf16 v[104:107], v[160:163], v[204:207], 0
	v_mfma_f32_16x16x32_bf16 v[92:95], v[152:155], v[212:215], 0
	v_mfma_f32_16x16x32_bf16 v[88:91], v[160:163], v[212:215], 0
	v_mfma_f32_16x16x32_bf16 v[76:79], v[152:155], v[220:223], 0
	v_mfma_f32_16x16x32_bf16 v[72:75], v[160:163], v[220:223], 0
	v_mfma_f32_16x16x32_bf16 v[124:127], v[156:159], v[200:203], v[124:127]
	v_mfma_f32_16x16x32_bf16 v[120:123], v[176:179], v[200:203], v[120:123]
	v_mfma_f32_16x16x32_bf16 v[108:111], v[156:159], v[208:211], v[108:111]
	v_mfma_f32_16x16x32_bf16 v[104:107], v[176:179], v[208:211], v[104:107]
	v_mfma_f32_16x16x32_bf16 v[92:95], v[156:159], v[216:219], v[92:95]
	v_mfma_f32_16x16x32_bf16 v[88:91], v[176:179], v[216:219], v[88:91]
	v_mfma_f32_16x16x32_bf16 v[76:79], v[156:159], v[224:227], v[76:79]
	v_mfma_f32_16x16x32_bf16 v[72:75], v[176:179], v[224:227], v[72:75]
	s_setprio 0
	s_setprio 1
	v_mfma_f32_16x16x32_bf16 v[116:119], v[180:183], v[196:199], 0
	v_mfma_f32_16x16x32_bf16 v[112:115], v[188:191], v[196:199], 0
	v_mfma_f32_16x16x32_bf16 v[100:103], v[180:183], v[204:207], 0
	v_mfma_f32_16x16x32_bf16 v[96:99], v[188:191], v[204:207], 0
	v_mfma_f32_16x16x32_bf16 v[84:87], v[180:183], v[212:215], 0
	v_mfma_f32_16x16x32_bf16 v[80:83], v[188:191], v[212:215], 0
	v_mfma_f32_16x16x32_bf16 v[68:71], v[180:183], v[220:223], 0
	v_mfma_f32_16x16x32_bf16 v[64:67], v[188:191], v[220:223], 0
	v_mfma_f32_16x16x32_bf16 v[116:119], v[184:187], v[200:203], v[116:119]
	v_mfma_f32_16x16x32_bf16 v[112:115], v[192:195], v[200:203], v[112:115]
	v_mfma_f32_16x16x32_bf16 v[100:103], v[184:187], v[208:211], v[100:103]
	v_mfma_f32_16x16x32_bf16 v[96:99], v[192:195], v[208:211], v[96:99]
	v_mfma_f32_16x16x32_bf16 v[84:87], v[184:187], v[216:219], v[84:87]
	v_mfma_f32_16x16x32_bf16 v[80:83], v[192:195], v[216:219], v[80:83]
	v_mfma_f32_16x16x32_bf16 v[68:71], v[184:187], v[224:227], v[68:71]
	v_mfma_f32_16x16x32_bf16 v[64:67], v[192:195], v[224:227], v[64:67]
	s_setprio 0
	s_barrier
	s_add_i32 s10, s34, s74
	v_lshl_add_u64 v[164:165], s[52:53], 0, v[130:131]
	s_mov_b32 m0, s10
	ds_read_b128 v[196:199], v171 offset:16384
	ds_read_b128 v[200:203], v171 offset:17408
	ds_read_b128 v[204:207], v171 offset:18432
	ds_read_b128 v[208:211], v171 offset:19456
	ds_read_b128 v[212:215], v171 offset:20480
	ds_read_b128 v[216:219], v171 offset:21504
	ds_read_b128 v[220:223], v171 offset:22528
	ds_read_b128 v[224:227], v171 offset:23552
	global_load_lds_dwordx4 v[164:165], off
	s_add_i32 m0, s10, 0x2000
	s_add_u32 s10, s52, 0x40000
	v_lshl_add_u64 v[228:229], s[52:53], 0, v[134:135]
	s_addc_u32 s11, s53, 0
	s_add_i32 s14, s35, s74
	global_load_lds_dwordx4 v[228:229], off
	v_lshl_add_u64 v[230:231], s[10:11], 0, v[130:131]
	s_mov_b32 m0, s14
	v_lshl_add_u64 v[232:233], s[66:67], 0, v[132:133]
	global_load_lds_dwordx4 v[230:231], off
	v_lshl_add_u64 v[230:231], s[10:11], 0, v[134:135]
	s_add_i32 m0, s14, 0x2000
	s_nop 0
	global_load_lds_dwordx4 v[230:231], off
	v_lshl_add_u64 v[230:231], s[66:67], 0, v[128:129]
	s_mov_b32 m0, s59
	s_nop 0
	global_load_lds_dwordx4 v[230:231], off
	s_mov_b32 m0, s75
	s_nop 0
	global_load_lds_dwordx4 v[232:233], off
	s_waitcnt vmcnt(8)
	s_waitcnt lgkmcnt(0)
	s_barrier
; #define PG8_STAGE(bufoff, gbase, voff) do { _Pragma("unroll") for (int _i = 0; _i < 2; ++_i) \
;         __builtin_amdgcn_global_load_lds((const unsigned*)((const char*)(gbase) + (voff)[_i]), (PG8_LAS unsigned*)(lds + (bufoff) + ldsw + _i * 8192), 16, 0, 0); } while (0)
; #define PG8_LDA(dst, b, h) do { _Pragma("unroll") for (int m = 0; m < 4; ++m) _Pragma("unroll") for (int k = 0; k < 2; ++k) dst[m][k] = *(const PG8_LAS bf16x8*)(lds + PG8_SA(b, h) + aoff + m * 2048 + k * 1024); } while (0)
; #define PG8_LDB(dst, b, h) do { _Pragma("unroll") for (int n = 0; n < 2; ++n) _Pragma("unroll") for (int k = 0; k < 2; ++k) dst[n][k] = *(const PG8_LAS bf16x8*)(lds + PG8_SB(b, h) + boff + n * 2048 + k * 1024); } while (0)
; #define PG8_MMA(ai, bj, At, Bt) do { __builtin_amdgcn_s_setprio(1); _Pragma("unroll") for (int m = 0; m < 4; ++m) _Pragma("unroll") for (int n = 0; n < 2; ++n) _Pragma("unroll") for (int k = 0; k < 2; ++k) \
;         acc[ai][bj][m][n] = __builtin_amdgcn_mfma_f32_16x16x32_bf16(Bt[n][k], At[m][k], acc[ai][bj][m][n], 0, 0, 0); __builtin_amdgcn_s_setprio(0); } while (0)
; #define PG8_WAIT_V(n) asm volatile("s_waitcnt vmcnt(" #n ")" ::: "memory")
; #define PG8_WAIT_L(n) asm volatile("s_waitcnt lgkmcnt(" #n ")" ::: "memory")
; #define PG8_BAR __builtin_amdgcn_s_barrier()
; #define PG8_SCHED __builtin_amdgcn_sched_barrier(0)
; template <class Epi, class Sched, bool ALIGN_EPI = false, bool SP2 = false, bool ABLK = false>
; __device__ __forceinline__ void gemm_phase(PG8_LAS unsigned char* lds, const Gemm g, const Sched& S, const Epi& E) {
;     ...
;             PG8_WAIT_V(8); PG8_WAIT_L(0); PG8_BAR; PG8_MMA(1, 0, At, B0); PG8_MMA(1, 1, At, B1); PG8_BAR; PG8_SCHED;
;             PG8_LDB(B0, 1, 0); PG8_LDB(B1, 1, 1); PG8_SCHED; PG8_LDA(At, 1, 0); PG8_STAGE(PG8_SA(0, 1), a2 + hstepA, voffA);
;             PG8_WAIT_V(8); PG8_WAIT_L(0); PG8_BAR; PG8_MMA(0, 0, At, B0); PG8_MMA(0, 1, At, B1); PG8_BAR; PG8_SCHED;
	s_setprio 1
	s_waitcnt lgkmcnt(0)
	v_mfma_f32_16x16x32_bf16 v[60:63], v[152:155], v[196:199], 0
	v_mfma_f32_16x16x32_bf16 v[56:59], v[160:163], v[196:199], 0
	v_mfma_f32_16x16x32_bf16 v[44:47], v[152:155], v[204:207], 0
	v_mfma_f32_16x16x32_bf16 v[40:43], v[160:163], v[204:207], 0
	v_mfma_f32_16x16x32_bf16 v[28:31], v[152:155], v[212:215], 0
	v_mfma_f32_16x16x32_bf16 v[24:27], v[160:163], v[212:215], 0
	v_mfma_f32_16x16x32_bf16 v[12:15], v[152:155], v[220:223], 0
	v_mfma_f32_16x16x32_bf16 v[8:11], v[160:163], v[220:223], 0
	v_mfma_f32_16x16x32_bf16 v[60:63], v[156:159], v[200:203], v[60:63]
	v_mfma_f32_16x16x32_bf16 v[56:59], v[176:179], v[200:203], v[56:59]
	v_mfma_f32_16x16x32_bf16 v[44:47], v[156:159], v[208:211], v[44:47]
	v_mfma_f32_16x16x32_bf16 v[40:43], v[176:179], v[208:211], v[40:43]
	v_mfma_f32_16x16x32_bf16 v[28:31], v[156:159], v[216:219], v[28:31]
	v_mfma_f32_16x16x32_bf16 v[24:27], v[176:179], v[216:219], v[24:27]
	v_mfma_f32_16x16x32_bf16 v[12:15], v[156:159], v[224:227], v[12:15]
	v_mfma_f32_16x16x32_bf16 v[8:11], v[176:179], v[224:227], v[8:11]
	s_setprio 0
	s_setprio 1
	v_mfma_f32_16x16x32_bf16 v[52:55], v[180:183], v[196:199], 0
	v_mfma_f32_16x16x32_bf16 v[48:51], v[188:191], v[196:199], 0
	v_mfma_f32_16x16x32_bf16 v[36:39], v[180:183], v[204:207], 0
	v_mfma_f32_16x16x32_bf16 v[32:35], v[188:191], v[204:207], 0
	v_mfma_f32_16x16x32_bf16 v[20:23], v[180:183], v[212:215], 0
	v_mfma_f32_16x16x32_bf16 v[16:19], v[188:191], v[212:215], 0
	v_mfma_f32_16x16x32_bf16 v[4:7], v[180:183], v[220:223], 0
	v_mfma_f32_16x16x32_bf16 v[0:3], v[188:191], v[220:223], 0
	v_mfma_f32_16x16x32_bf16 v[52:55], v[184:187], v[200:203], v[52:55]
	v_mfma_f32_16x16x32_bf16 v[48:51], v[192:195], v[200:203], v[48:51]
	v_mfma_f32_16x16x32_bf16 v[36:39], v[184:187], v[208:211], v[36:39]
	v_mfma_f32_16x16x32_bf16 v[32:35], v[192:195], v[208:211], v[32:35]
	v_mfma_f32_16x16x32_bf16 v[20:23], v[184:187], v[216:219], v[20:23]
	v_mfma_f32_16x16x32_bf16 v[16:19], v[192:195], v[216:219], v[16:19]
	v_mfma_f32_16x16x32_bf16 v[4:7], v[184:187], v[224:227], v[4:7]
	v_mfma_f32_16x16x32_bf16 v[0:3], v[192:195], v[224:227], v[0:3]
	s_setprio 0
	s_barrier
	s_add_i32 s14, 0, 0x18000
	v_add_u32_e32 v175, s14, v168
	s_add_i32 s15, 0, 0x1c000
	ds_read_b128 v[152:155], v175
	ds_read_b128 v[156:159], v175 offset:1024
	ds_read_b128 v[160:163], v175 offset:2048
	ds_read_b128 v[176:179], v175 offset:3072
	v_add_u32_e32 v175, s15, v168
	ds_read_b128 v[180:183], v175
	ds_read_b128 v[184:187], v175 offset:1024
	ds_read_b128 v[188:191], v175 offset:2048
	ds_read_b128 v[192:195], v175 offset:3072
	s_add_u32 s10, s66, 0x40000
	s_addc_u32 s11, s67, 0
	s_mov_b32 m0, s81
	v_lshl_add_u64 v[234:235], s[10:11], 0, v[128:129]
	ds_read_b128 v[196:199], v171 offset:32768
	ds_read_b128 v[200:203], v171 offset:33792
	ds_read_b128 v[204:207], v171 offset:34816
	ds_read_b128 v[208:211], v171 offset:35840
	ds_read_b128 v[212:215], v171 offset:36864
	ds_read_b128 v[216:219], v171 offset:37888
	ds_read_b128 v[220:223], v171 offset:38912
	ds_read_b128 v[224:227], v171 offset:39936
	global_load_lds_dwordx4 v[234:235], off
	v_lshl_add_u64 v[234:235], s[10:11], 0, v[132:133]
	s_mov_b32 m0, s12
	s_nop 0
	global_load_lds_dwordx4 v[234:235], off
	s_waitcnt vmcnt(8)
	s_waitcnt lgkmcnt(0)
	s_barrier
	s_setprio 1
	s_waitcnt lgkmcnt(0)
	v_mfma_f32_16x16x32_bf16 v[124:127], v[152:155], v[196:199], v[124:127]
	v_mfma_f32_16x16x32_bf16 v[120:123], v[160:163], v[196:199], v[120:123]
	v_mfma_f32_16x16x32_bf16 v[108:111], v[152:155], v[204:207], v[108:111]
	v_mfma_f32_16x16x32_bf16 v[104:107], v[160:163], v[204:207], v[104:107]
	v_mfma_f32_16x16x32_bf16 v[92:95], v[152:155], v[212:215], v[92:95]
	v_mfma_f32_16x16x32_bf16 v[88:91], v[160:163], v[212:215], v[88:91]
	v_mfma_f32_16x16x32_bf16 v[76:79], v[152:155], v[220:223], v[76:79]
	v_mfma_f32_16x16x32_bf16 v[72:75], v[160:163], v[220:223], v[72:75]
	v_mfma_f32_16x16x32_bf16 v[124:127], v[156:159], v[200:203], v[124:127]
	v_mfma_f32_16x16x32_bf16 v[120:123], v[176:179], v[200:203], v[120:123]
	v_mfma_f32_16x16x32_bf16 v[108:111], v[156:159], v[208:211], v[108:111]
	v_mfma_f32_16x16x32_bf16 v[104:107], v[176:179], v[208:211], v[104:107]
	v_mfma_f32_16x16x32_bf16 v[92:95], v[156:159], v[216:219], v[92:95]
	v_mfma_f32_16x16x32_bf16 v[88:91], v[176:179], v[216:219], v[88:91]
	v_mfma_f32_16x16x32_bf16 v[76:79], v[156:159], v[224:227], v[76:79]
	v_mfma_f32_16x16x32_bf16 v[72:75], v[176:179], v[224:227], v[72:75]
	s_setprio 0
	s_setprio 1
	v_mfma_f32_16x16x32_bf16 v[116:119], v[180:183], v[196:199], v[116:119]
	v_mfma_f32_16x16x32_bf16 v[112:115], v[188:191], v[196:199], v[112:115]
	v_mfma_f32_16x16x32_bf16 v[100:103], v[180:183], v[204:207], v[100:103]
	v_mfma_f32_16x16x32_bf16 v[96:99], v[188:191], v[204:207], v[96:99]
	v_mfma_f32_16x16x32_bf16 v[84:87], v[180:183], v[212:215], v[84:87]
	v_mfma_f32_16x16x32_bf16 v[80:83], v[188:191], v[212:215], v[80:83]
	v_mfma_f32_16x16x32_bf16 v[68:71], v[180:183], v[220:223], v[68:71]
	v_mfma_f32_16x16x32_bf16 v[64:67], v[188:191], v[220:223], v[64:67]
	v_mfma_f32_16x16x32_bf16 v[116:119], v[184:187], v[200:203], v[116:119]
	v_mfma_f32_16x16x32_bf16 v[112:115], v[192:195], v[200:203], v[112:115]
	v_mfma_f32_16x16x32_bf16 v[100:103], v[184:187], v[208:211], v[100:103]
	v_mfma_f32_16x16x32_bf16 v[96:99], v[192:195], v[208:211], v[96:99]
	v_mfma_f32_16x16x32_bf16 v[84:87], v[184:187], v[216:219], v[84:87]
	v_mfma_f32_16x16x32_bf16 v[80:83], v[192:195], v[216:219], v[80:83]
	v_mfma_f32_16x16x32_bf16 v[68:71], v[184:187], v[224:227], v[68:71]
	v_mfma_f32_16x16x32_bf16 v[64:67], v[192:195], v[224:227], v[64:67]
	s_setprio 0
	s_barrier
; #define PG8_STAGE(bufoff, gbase, voff) do { _Pragma("unroll") for (int _i = 0; _i < 2; ++_i) \
;         __builtin_amdgcn_global_load_lds((const unsigned*)((const char*)(gbase) + (voff)[_i]), (PG8_LAS unsigned*)(lds + (bufoff) + ldsw + _i * 8192), 16, 0, 0); } while (0)
; #define PG8_LDA(dst, b, h) do { _Pragma("unroll") for (int m = 0; m < 4; ++m) _Pragma("unroll") for (int k = 0; k < 2; ++k) dst[m][k] = *(const PG8_LAS bf16x8*)(lds + PG8_SA(b, h) + aoff + m * 2048 + k * 1024); } while (0)
; #define PG8_MMA(ai, bj, At, Bt) do { __builtin_amdgcn_s_setprio(1); _Pragma("unroll") for (int m = 0; m < 4; ++m) _Pragma("unroll") for (int n = 0; n < 2; ++n) _Pragma("unroll") for (int k = 0; k < 2; ++k) \
;         acc[ai][bj][m][n] = __builtin_amdgcn_mfma_f32_16x16x32_bf16(Bt[n][k], At[m][k], acc[ai][bj][m][n], 0, 0, 0); __builtin_amdgcn_s_setprio(0); } while (0)
; #define PG8_WAIT_V(n) asm volatile("s_waitcnt vmcnt(" #n ")" ::: "memory")
; #define PG8_WAIT_L(n) asm volatile("s_waitcnt lgkmcnt(" #n ")" ::: "memory")
; #define PG8_BAR __builtin_amdgcn_s_barrier()
; #define PG8_SCHED __builtin_amdgcn_sched_barrier(0)
; template <class Epi, class Sched, bool ALIGN_EPI = false, bool SP2 = false, bool ABLK = false>
; __device__ __forceinline__ void gemm_phase(PG8_LAS unsigned char* lds, const Gemm g, const Sched& S, const Epi& E) {
;     ...
;             PG8_WAIT_V(8); PG8_WAIT_L(0); PG8_BAR; PG8_MMA(0, 0, At, B0); PG8_MMA(0, 1, At, B1); PG8_BAR; PG8_SCHED;
;             PG8_LDA(At, 1, 1); PG8_STAGE(PG8_SB(1, 0), b3, voffB); PG8_STAGE(PG8_SB(1, 1), b3 + hstep, voffB); PG8_STAGE(PG8_SA(1, 0), a3, voffA);
;             PG8_WAIT_V(8); PG8_WAIT_L(0); PG8_BAR; PG8_MMA(1, 0, At, B0); PG8_MMA(1, 1, At, B1); PG8_BAR; PG8_SCHED;
	s_add_i32 s10, s14, s74
	v_lshl_add_u64 v[164:165], v[164:165], 0, s[28:29]
	s_mov_b32 m0, s10
	ds_read_b128 v[196:199], v171 offset:49152
	ds_read_b128 v[200:203], v171 offset:50176
	ds_read_b128 v[204:207], v171 offset:51200
	ds_read_b128 v[208:211], v171 offset:52224
	ds_read_b128 v[212:215], v171 offset:53248
	ds_read_b128 v[216:219], v171 offset:54272
	ds_read_b128 v[220:223], v171 offset:55296
	ds_read_b128 v[224:227], v171 offset:56320
	global_load_lds_dwordx4 v[164:165], off
	s_add_i32 m0, s10, 0x2000
	s_add_u32 s10, s52, 0x40080
	v_lshl_add_u64 v[164:165], v[228:229], 0, s[28:29]
	s_addc_u32 s11, s53, 0
	s_add_i32 s14, s15, s74
	global_load_lds_dwordx4 v[164:165], off
	v_lshl_add_u64 v[164:165], s[10:11], 0, v[130:131]
	s_mov_b32 m0, s14
	s_nop 0
	global_load_lds_dwordx4 v[164:165], off
	v_lshl_add_u64 v[164:165], s[10:11], 0, v[134:135]
	s_add_i32 m0, s14, 0x2000
	s_nop 0
	global_load_lds_dwordx4 v[164:165], off
	v_lshl_add_u64 v[164:165], v[230:231], 0, s[28:29]
	s_mov_b32 m0, s50
	s_nop 0
	global_load_lds_dwordx4 v[164:165], off
	v_lshl_add_u64 v[164:165], v[232:233], 0, s[28:29]
	s_mov_b32 m0, s51
	s_nop 0
	global_load_lds_dwordx4 v[164:165], off
	s_waitcnt vmcnt(8)
	s_waitcnt lgkmcnt(0)
	s_barrier
	s_setprio 1
	s_waitcnt lgkmcnt(0)
	v_mfma_f32_16x16x32_bf16 v[60:63], v[152:155], v[196:199], v[60:63]
	v_mfma_f32_16x16x32_bf16 v[56:59], v[160:163], v[196:199], v[56:59]
	v_mfma_f32_16x16x32_bf16 v[44:47], v[152:155], v[204:207], v[44:47]
	v_mfma_f32_16x16x32_bf16 v[40:43], v[160:163], v[204:207], v[40:43]
	v_mfma_f32_16x16x32_bf16 v[28:31], v[152:155], v[212:215], v[28:31]
	v_mfma_f32_16x16x32_bf16 v[24:27], v[160:163], v[212:215], v[24:27]
	v_mfma_f32_16x16x32_bf16 v[12:15], v[152:155], v[220:223], v[12:15]
	v_mfma_f32_16x16x32_bf16 v[8:11], v[160:163], v[220:223], v[8:11]
	v_mfma_f32_16x16x32_bf16 v[60:63], v[156:159], v[200:203], v[60:63]
	v_mfma_f32_16x16x32_bf16 v[56:59], v[176:179], v[200:203], v[56:59]
	v_mfma_f32_16x16x32_bf16 v[44:47], v[156:159], v[208:211], v[44:47]
	v_mfma_f32_16x16x32_bf16 v[40:43], v[176:179], v[208:211], v[40:43]
	v_mfma_f32_16x16x32_bf16 v[28:31], v[156:159], v[216:219], v[28:31]
	v_mfma_f32_16x16x32_bf16 v[24:27], v[176:179], v[216:219], v[24:27]
	v_mfma_f32_16x16x32_bf16 v[12:15], v[156:159], v[224:227], v[12:15]
	v_mfma_f32_16x16x32_bf16 v[8:11], v[176:179], v[224:227], v[8:11]
	s_setprio 0
	s_setprio 1
	v_mfma_f32_16x16x32_bf16 v[52:55], v[180:183], v[196:199], v[52:55]
	v_mfma_f32_16x16x32_bf16 v[48:51], v[188:191], v[196:199], v[48:51]
	v_mfma_f32_16x16x32_bf16 v[36:39], v[180:183], v[204:207], v[36:39]
	v_mfma_f32_16x16x32_bf16 v[32:35], v[188:191], v[204:207], v[32:35]
	v_mfma_f32_16x16x32_bf16 v[20:23], v[180:183], v[212:215], v[20:23]
	v_mfma_f32_16x16x32_bf16 v[16:19], v[188:191], v[212:215], v[16:19]
	v_mfma_f32_16x16x32_bf16 v[4:7], v[180:183], v[220:223], v[4:7]
	v_mfma_f32_16x16x32_bf16 v[0:3], v[188:191], v[220:223], v[0:3]
	v_mfma_f32_16x16x32_bf16 v[52:55], v[184:187], v[200:203], v[52:55]
	v_mfma_f32_16x16x32_bf16 v[48:51], v[192:195], v[200:203], v[48:51]
	v_mfma_f32_16x16x32_bf16 v[36:39], v[184:187], v[208:211], v[36:39]
	v_mfma_f32_16x16x32_bf16 v[32:35], v[192:195], v[208:211], v[32:35]
	v_mfma_f32_16x16x32_bf16 v[20:23], v[184:187], v[216:219], v[20:23]
	v_mfma_f32_16x16x32_bf16 v[16:19], v[192:195], v[216:219], v[16:19]
	v_mfma_f32_16x16x32_bf16 v[4:7], v[184:187], v[224:227], v[4:7]
	v_mfma_f32_16x16x32_bf16 v[0:3], v[192:195], v[224:227], v[0:3]
	s_setprio 0
	s_barrier
	s_add_i32 s9, s9, 2
	s_add_u32 s42, s42, 0x100
	s_addc_u32 s43, s43, 0
	s_add_u32 s7, s7, 0x100
	s_addc_u32 s8, s8, 0
	s_cmp_gt_u32 s9, 13
	s_cbranch_scc1 .Lpeel_post_2

; #define PG8_BAR __builtin_amdgcn_s_barrier()
; template <class Epi, class Sched, bool ALIGN_EPI = false, bool SP2 = false, bool ABLK = false>
; __device__ __forceinline__ void gemm_phase(PG8_LAS unsigned char* lds, const Gemm g, const Sched& S, const Epi& E) {
;     ...
;         if constexpr (ALIGN_EPI) { if (wr == 0) PG8_BAR; }
.Lpeel_post_2:
	s_and_b64 vcc, exec, s[30:31]
	s_cbranch_vccz .LBB0_348
	s_barrier

; #define PG8_STAGE(bufoff, gbase, voff) do { _Pragma("unroll") for (int _i = 0; _i < 2; ++_i) \
;         __builtin_amdgcn_global_load_lds((const unsigned*)((const char*)(gbase) + (voff)[_i]), (PG8_LAS unsigned*)(lds + (bufoff) + ldsw + _i * 8192), 16, 0, 0); } while (0)
; #define PG8_LDA(dst, b, h) do { _Pragma("unroll") for (int m = 0; m < 4; ++m) _Pragma("unroll") for (int k = 0; k < 2; ++k) dst[m][k] = *(const PG8_LAS bf16x8*)(lds + PG8_SA(b, h) + aoff + m * 2048 + k * 1024); } while (0)
; #define PG8_LDB(dst, b, h) do { _Pragma("unroll") for (int n = 0; n < 2; ++n) _Pragma("unroll") for (int k = 0; k < 2; ++k) dst[n][k] = *(const PG8_LAS bf16x8*)(lds + PG8_SB(b, h) + boff + n * 2048 + k * 1024); } while (0)
; #define PG8_MMA(ai, bj, At, Bt) do { __builtin_amdgcn_s_setprio(1); _Pragma("unroll") for (int m = 0; m < 4; ++m) _Pragma("unroll") for (int n = 0; n < 2; ++n) _Pragma("unroll") for (int k = 0; k < 2; ++k) \
;         acc[ai][bj][m][n] = __builtin_amdgcn_mfma_f32_16x16x32_bf16(Bt[n][k], At[m][k], acc[ai][bj][m][n], 0, 0, 0); __builtin_amdgcn_s_setprio(0); } while (0)
; #define PG8_WAIT_V(n) asm volatile("s_waitcnt vmcnt(" #n ")" ::: "memory")
; #define PG8_WAIT_L(n) asm volatile("s_waitcnt lgkmcnt(" #n ")" ::: "memory")
; #define PG8_BAR __builtin_amdgcn_s_barrier()
; #define PG8_SCHED __builtin_amdgcn_sched_barrier(0)
; template <class Epi, class Sched, bool ALIGN_EPI = false, bool SP2 = false, bool ABLK = false>
; __device__ __forceinline__ void gemm_phase(PG8_LAS unsigned char* lds, const Gemm g, const Sched& S, const Epi& E) {
;     ...
;             PG8_LDB(B0, 0, 0); PG8_LDB(B1, 0, 1); PG8_SCHED; PG8_LDA(At, 0, 0); PG8_STAGE(PG8_SA(1, 1), a1 + hstepA, voffA);
;             PG8_WAIT_V(8); PG8_WAIT_L(0); PG8_BAR; PG8_MMA(0, 0, At, B0); PG8_MMA(0, 1, At, B1); PG8_BAR; PG8_SCHED;
;             PG8_LDA(At, 0, 1); PG8_STAGE(PG8_SB(0, 0), b2, voffB); PG8_STAGE(PG8_SB(0, 1), b2 + hstep, voffB); PG8_STAGE(PG8_SA(0, 0), a2, voffA);
;             PG8_WAIT_V(8); PG8_WAIT_L(0); PG8_BAR; PG8_MMA(1, 0, At, B0); PG8_MMA(1, 1, At, B1); PG8_BAR; PG8_SCHED;
;     ...
; #pragma unroll
;         for (int a = 0; a < 2; ++a)
; #pragma unroll
;             for (int b = 0; b < 2; ++b)
; #pragma unroll
;                 for (int m = 0; m < 4; ++m)
; #pragma unroll
;                     for (int n = 0; n < 2; ++n) acc[a][b][m][n] = (f32x4){0.f, 0.f, 0.f, 0.f};
.LBB0_824:
	ds_read_b128 v[156:159], v162
	ds_read_b128 v[168:171], v162 offset:1024
	ds_read_b128 v[172:175], v162 offset:2048
	ds_read_b128 v[176:179], v162 offset:3072
	ds_read_b128 v[180:183], v163
	ds_read_b128 v[184:187], v163 offset:1024
	ds_read_b128 v[188:191], v163 offset:2048
	ds_read_b128 v[192:195], v163 offset:3072
	s_add_u32 s11, s36, 0xfffc0080
	s_addc_u32 s14, s37, -1
	s_cmp_eq_u32 s10, 12
	s_cselect_b32 s53, s4, s14
	s_cselect_b32 s52, s5, s11
	s_cselect_b32 s51, s6, s9
	s_cselect_b32 s50, s7, s8
	v_lshl_add_u64 v[228:229], s[36:37], 0, v[148:149]
	s_add_i32 m0, s58, 0xc000
	ds_read_b128 v[196:199], v164
	ds_read_b128 v[200:203], v164 offset:1024
	ds_read_b128 v[204:207], v164 offset:2048
	ds_read_b128 v[208:211], v164 offset:3072
	ds_read_b128 v[212:215], v164 offset:4096
	ds_read_b128 v[216:219], v164 offset:5120
	ds_read_b128 v[220:223], v164 offset:6144
	ds_read_b128 v[224:227], v164 offset:7168
	global_load_lds_dwordx4 v[228:229], off
	v_lshl_add_u64 v[228:229], s[36:37], 0, v[150:151]
	s_add_i32 m0, s58, 0xe000
	s_nop 0
	global_load_lds_dwordx4 v[228:229], off
	s_waitcnt vmcnt(8)
	s_waitcnt lgkmcnt(0)
	s_barrier
	s_setprio 1
	s_waitcnt lgkmcnt(0)
	v_mfma_f32_16x16x32_bf16 v[124:127], v[156:159], v[196:199], 0
	v_mfma_f32_16x16x32_bf16 v[120:123], v[172:175], v[196:199], 0
	v_mfma_f32_16x16x32_bf16 v[108:111], v[156:159], v[204:207], 0
	v_mfma_f32_16x16x32_bf16 v[104:107], v[172:175], v[204:207], 0
	v_mfma_f32_16x16x32_bf16 v[92:95], v[156:159], v[212:215], 0
	v_mfma_f32_16x16x32_bf16 v[88:91], v[172:175], v[212:215], 0
	v_mfma_f32_16x16x32_bf16 v[76:79], v[156:159], v[220:223], 0
	v_mfma_f32_16x16x32_bf16 v[72:75], v[172:175], v[220:223], 0
	v_mfma_f32_16x16x32_bf16 v[124:127], v[168:171], v[200:203], v[124:127]
	v_mfma_f32_16x16x32_bf16 v[120:123], v[176:179], v[200:203], v[120:123]
	v_mfma_f32_16x16x32_bf16 v[108:111], v[168:171], v[208:211], v[108:111]
	v_mfma_f32_16x16x32_bf16 v[104:107], v[176:179], v[208:211], v[104:107]
	v_mfma_f32_16x16x32_bf16 v[92:95], v[168:171], v[216:219], v[92:95]
	v_mfma_f32_16x16x32_bf16 v[88:91], v[176:179], v[216:219], v[88:91]
	v_mfma_f32_16x16x32_bf16 v[76:79], v[168:171], v[224:227], v[76:79]
	v_mfma_f32_16x16x32_bf16 v[72:75], v[176:179], v[224:227], v[72:75]
	s_setprio 0
	s_setprio 1
	v_mfma_f32_16x16x32_bf16 v[116:119], v[180:183], v[196:199], 0
	v_mfma_f32_16x16x32_bf16 v[112:115], v[188:191], v[196:199], 0
	v_mfma_f32_16x16x32_bf16 v[100:103], v[180:183], v[204:207], 0
	v_mfma_f32_16x16x32_bf16 v[96:99], v[188:191], v[204:207], 0
	v_mfma_f32_16x16x32_bf16 v[84:87], v[180:183], v[212:215], 0
	v_mfma_f32_16x16x32_bf16 v[80:83], v[188:191], v[212:215], 0
	v_mfma_f32_16x16x32_bf16 v[68:71], v[180:183], v[220:223], 0
	v_mfma_f32_16x16x32_bf16 v[64:67], v[188:191], v[220:223], 0
	v_mfma_f32_16x16x32_bf16 v[116:119], v[184:187], v[200:203], v[116:119]
	v_mfma_f32_16x16x32_bf16 v[112:115], v[192:195], v[200:203], v[112:115]
	v_mfma_f32_16x16x32_bf16 v[100:103], v[184:187], v[208:211], v[100:103]
	v_mfma_f32_16x16x32_bf16 v[96:99], v[192:195], v[208:211], v[96:99]
	v_mfma_f32_16x16x32_bf16 v[84:87], v[184:187], v[216:219], v[84:87]
	v_mfma_f32_16x16x32_bf16 v[80:83], v[192:195], v[216:219], v[80:83]
	v_mfma_f32_16x16x32_bf16 v[68:71], v[184:187], v[224:227], v[68:71]
	v_mfma_f32_16x16x32_bf16 v[64:67], v[192:195], v[224:227], v[64:67]
	s_setprio 0
	s_barrier
	s_add_i32 s11, s70, s54
	v_lshl_add_u64 v[228:229], s[50:51], 0, v[132:133]
	s_mov_b32 m0, s11
	ds_read_b128 v[196:199], v164 offset:16384
	ds_read_b128 v[200:203], v164 offset:17408
	ds_read_b128 v[204:207], v164 offset:18432
	ds_read_b128 v[208:211], v164 offset:19456
	ds_read_b128 v[212:215], v164 offset:20480
	ds_read_b128 v[216:219], v164 offset:21504
	ds_read_b128 v[220:223], v164 offset:22528
	ds_read_b128 v[224:227], v164 offset:23552
	global_load_lds_dwordx4 v[228:229], off
	s_add_i32 m0, s11, 0x2000
	s_add_u32 s14, s50, 0x40000
	v_lshl_add_u64 v[230:231], s[50:51], 0, v[128:129]
	s_addc_u32 s15, s51, 0
	s_add_i32 s11, s71, s54
	global_load_lds_dwordx4 v[230:231], off
	v_lshl_add_u64 v[232:233], s[14:15], 0, v[132:133]
	s_mov_b32 m0, s11
	v_lshl_add_u64 v[234:235], s[52:53], 0, v[130:131]
	global_load_lds_dwordx4 v[232:233], off
	v_lshl_add_u64 v[232:233], s[14:15], 0, v[128:129]
	s_add_i32 m0, s11, 0x2000
	s_nop 0
	global_load_lds_dwordx4 v[232:233], off
	v_lshl_add_u64 v[232:233], s[52:53], 0, v[134:135]
	s_mov_b32 m0, s58
	s_nop 0
	global_load_lds_dwordx4 v[232:233], off
	s_mov_b32 m0, s59
	s_nop 0
	global_load_lds_dwordx4 v[234:235], off
	s_waitcnt vmcnt(8)
	s_waitcnt lgkmcnt(0)
	s_barrier
; #define PG8_STAGE(bufoff, gbase, voff) do { _Pragma("unroll") for (int _i = 0; _i < 2; ++_i) \
;         __builtin_amdgcn_global_load_lds((const unsigned*)((const char*)(gbase) + (voff)[_i]), (PG8_LAS unsigned*)(lds + (bufoff) + ldsw + _i * 8192), 16, 0, 0); } while (0)
; #define PG8_LDA(dst, b, h) do { _Pragma("unroll") for (int m = 0; m < 4; ++m) _Pragma("unroll") for (int k = 0; k < 2; ++k) dst[m][k] = *(const PG8_LAS bf16x8*)(lds + PG8_SA(b, h) + aoff + m * 2048 + k * 1024); } while (0)
; #define PG8_LDB(dst, b, h) do { _Pragma("unroll") for (int n = 0; n < 2; ++n) _Pragma("unroll") for (int k = 0; k < 2; ++k) dst[n][k] = *(const PG8_LAS bf16x8*)(lds + PG8_SB(b, h) + boff + n * 2048 + k * 1024); } while (0)
; #define PG8_MMA(ai, bj, At, Bt) do { __builtin_amdgcn_s_setprio(1); _Pragma("unroll") for (int m = 0; m < 4; ++m) _Pragma("unroll") for (int n = 0; n < 2; ++n) _Pragma("unroll") for (int k = 0; k < 2; ++k) \
;         acc[ai][bj][m][n] = __builtin_amdgcn_mfma_f32_16x16x32_bf16(Bt[n][k], At[m][k], acc[ai][bj][m][n], 0, 0, 0); __builtin_amdgcn_s_setprio(0); } while (0)
; #define PG8_WAIT_V(n) asm volatile("s_waitcnt vmcnt(" #n ")" ::: "memory")
; #define PG8_WAIT_L(n) asm volatile("s_waitcnt lgkmcnt(" #n ")" ::: "memory")
; #define PG8_BAR __builtin_amdgcn_s_barrier()
; #define PG8_SCHED __builtin_amdgcn_sched_barrier(0)
; template <class Epi, class Sched, bool ALIGN_EPI = false, bool SP2 = false, bool ABLK = false>
; __device__ __forceinline__ void gemm_phase(PG8_LAS unsigned char* lds, const Gemm g, const Sched& S, const Epi& E) {
;     ...
;             PG8_WAIT_V(8); PG8_WAIT_L(0); PG8_BAR; PG8_MMA(1, 0, At, B0); PG8_MMA(1, 1, At, B1); PG8_BAR; PG8_SCHED;
;             PG8_LDB(B0, 1, 0); PG8_LDB(B1, 1, 1); PG8_SCHED; PG8_LDA(At, 1, 0); PG8_STAGE(PG8_SA(0, 1), a2 + hstepA, voffA);
;             PG8_WAIT_V(8); PG8_WAIT_L(0); PG8_BAR; PG8_MMA(0, 0, At, B0); PG8_MMA(0, 1, At, B1); PG8_BAR; PG8_SCHED;
	s_setprio 1
	s_waitcnt lgkmcnt(0)
	v_mfma_f32_16x16x32_bf16 v[60:63], v[156:159], v[196:199], 0
	v_mfma_f32_16x16x32_bf16 v[56:59], v[172:175], v[196:199], 0
	v_mfma_f32_16x16x32_bf16 v[44:47], v[156:159], v[204:207], 0
	v_mfma_f32_16x16x32_bf16 v[40:43], v[172:175], v[204:207], 0
	v_mfma_f32_16x16x32_bf16 v[28:31], v[156:159], v[212:215], 0
	v_mfma_f32_16x16x32_bf16 v[24:27], v[172:175], v[212:215], 0
	v_mfma_f32_16x16x32_bf16 v[12:15], v[156:159], v[220:223], 0
	v_mfma_f32_16x16x32_bf16 v[8:11], v[172:175], v[220:223], 0
	v_mfma_f32_16x16x32_bf16 v[60:63], v[168:171], v[200:203], v[60:63]
	v_mfma_f32_16x16x32_bf16 v[56:59], v[176:179], v[200:203], v[56:59]
	v_mfma_f32_16x16x32_bf16 v[44:47], v[168:171], v[208:211], v[44:47]
	v_mfma_f32_16x16x32_bf16 v[40:43], v[176:179], v[208:211], v[40:43]
	v_mfma_f32_16x16x32_bf16 v[28:31], v[168:171], v[216:219], v[28:31]
	v_mfma_f32_16x16x32_bf16 v[24:27], v[176:179], v[216:219], v[24:27]
	v_mfma_f32_16x16x32_bf16 v[12:15], v[168:171], v[224:227], v[12:15]
	v_mfma_f32_16x16x32_bf16 v[8:11], v[176:179], v[224:227], v[8:11]
	s_setprio 0
	s_setprio 1
	v_mfma_f32_16x16x32_bf16 v[52:55], v[180:183], v[196:199], 0
	v_mfma_f32_16x16x32_bf16 v[48:51], v[188:191], v[196:199], 0
	v_mfma_f32_16x16x32_bf16 v[36:39], v[180:183], v[204:207], 0
	v_mfma_f32_16x16x32_bf16 v[32:35], v[188:191], v[204:207], 0
	v_mfma_f32_16x16x32_bf16 v[20:23], v[180:183], v[212:215], 0
	v_mfma_f32_16x16x32_bf16 v[16:19], v[188:191], v[212:215], 0
	v_mfma_f32_16x16x32_bf16 v[4:7], v[180:183], v[220:223], 0
	v_mfma_f32_16x16x32_bf16 v[0:3], v[188:191], v[220:223], 0
	v_mfma_f32_16x16x32_bf16 v[52:55], v[184:187], v[200:203], v[52:55]
	v_mfma_f32_16x16x32_bf16 v[48:51], v[192:195], v[200:203], v[48:51]
	v_mfma_f32_16x16x32_bf16 v[36:39], v[184:187], v[208:211], v[36:39]
	v_mfma_f32_16x16x32_bf16 v[32:35], v[192:195], v[208:211], v[32:35]
	v_mfma_f32_16x16x32_bf16 v[20:23], v[184:187], v[216:219], v[20:23]
	v_mfma_f32_16x16x32_bf16 v[16:19], v[192:195], v[216:219], v[16:19]
	v_mfma_f32_16x16x32_bf16 v[4:7], v[184:187], v[224:227], v[4:7]
	v_mfma_f32_16x16x32_bf16 v[0:3], v[192:195], v[224:227], v[0:3]
	s_setprio 0
	s_barrier
	s_add_i32 s11, 0, 0x18000
	s_add_i32 s16, 0, 0x1c000
	v_add_u32_e32 v176, s11, v161
	v_add_u32_e32 v192, s16, v161
	ds_read_b128 v[156:159], v176
	ds_read_b128 v[168:171], v176 offset:1024
	ds_read_b128 v[172:175], v176 offset:2048
	ds_read_b128 v[176:179], v176 offset:3072
	ds_read_b128 v[180:183], v192
	ds_read_b128 v[184:187], v192 offset:1024
	ds_read_b128 v[188:191], v192 offset:2048
	ds_read_b128 v[192:195], v192 offset:3072
	s_add_u32 s14, s52, 0x40000
	s_addc_u32 s15, s53, 0
	s_mov_b32 m0, s60
	v_lshl_add_u64 v[236:237], s[14:15], 0, v[134:135]
	ds_read_b128 v[196:199], v164 offset:32768
	ds_read_b128 v[200:203], v164 offset:33792
	ds_read_b128 v[204:207], v164 offset:34816
	ds_read_b128 v[208:211], v164 offset:35840
	ds_read_b128 v[212:215], v164 offset:36864
	ds_read_b128 v[216:219], v164 offset:37888
	ds_read_b128 v[220:223], v164 offset:38912
	ds_read_b128 v[224:227], v164 offset:39936
	global_load_lds_dwordx4 v[236:237], off
	v_lshl_add_u64 v[236:237], s[14:15], 0, v[130:131]
	s_mov_b32 m0, s61
	s_nop 0
	global_load_lds_dwordx4 v[236:237], off
	s_waitcnt vmcnt(8)
	s_waitcnt lgkmcnt(0)
	s_barrier
	s_setprio 1
	s_waitcnt lgkmcnt(0)
	v_mfma_f32_16x16x32_bf16 v[124:127], v[156:159], v[196:199], v[124:127]
	v_mfma_f32_16x16x32_bf16 v[120:123], v[172:175], v[196:199], v[120:123]
	v_mfma_f32_16x16x32_bf16 v[108:111], v[156:159], v[204:207], v[108:111]
	v_mfma_f32_16x16x32_bf16 v[104:107], v[172:175], v[204:207], v[104:107]
	v_mfma_f32_16x16x32_bf16 v[92:95], v[156:159], v[212:215], v[92:95]
	v_mfma_f32_16x16x32_bf16 v[88:91], v[172:175], v[212:215], v[88:91]
	v_mfma_f32_16x16x32_bf16 v[76:79], v[156:159], v[220:223], v[76:79]
	v_mfma_f32_16x16x32_bf16 v[72:75], v[172:175], v[220:223], v[72:75]
	v_mfma_f32_16x16x32_bf16 v[124:127], v[168:171], v[200:203], v[124:127]
	v_mfma_f32_16x16x32_bf16 v[120:123], v[176:179], v[200:203], v[120:123]
	v_mfma_f32_16x16x32_bf16 v[108:111], v[168:171], v[208:211], v[108:111]
	v_mfma_f32_16x16x32_bf16 v[104:107], v[176:179], v[208:211], v[104:107]
	v_mfma_f32_16x16x32_bf16 v[92:95], v[168:171], v[216:219], v[92:95]
	v_mfma_f32_16x16x32_bf16 v[88:91], v[176:179], v[216:219], v[88:91]
	v_mfma_f32_16x16x32_bf16 v[76:79], v[168:171], v[224:227], v[76:79]
	v_mfma_f32_16x16x32_bf16 v[72:75], v[176:179], v[224:227], v[72:75]
	s_setprio 0
	s_setprio 1
	v_mfma_f32_16x16x32_bf16 v[116:119], v[180:183], v[196:199], v[116:119]
	v_mfma_f32_16x16x32_bf16 v[112:115], v[188:191], v[196:199], v[112:115]
	v_mfma_f32_16x16x32_bf16 v[100:103], v[180:183], v[204:207], v[100:103]
	v_mfma_f32_16x16x32_bf16 v[96:99], v[188:191], v[204:207], v[96:99]
	v_mfma_f32_16x16x32_bf16 v[84:87], v[180:183], v[212:215], v[84:87]
	v_mfma_f32_16x16x32_bf16 v[80:83], v[188:191], v[212:215], v[80:83]
	v_mfma_f32_16x16x32_bf16 v[68:71], v[180:183], v[220:223], v[68:71]
	v_mfma_f32_16x16x32_bf16 v[64:67], v[188:191], v[220:223], v[64:67]
	v_mfma_f32_16x16x32_bf16 v[116:119], v[184:187], v[200:203], v[116:119]
	v_mfma_f32_16x16x32_bf16 v[112:115], v[192:195], v[200:203], v[112:115]
	v_mfma_f32_16x16x32_bf16 v[100:103], v[184:187], v[208:211], v[100:103]
	v_mfma_f32_16x16x32_bf16 v[96:99], v[192:195], v[208:211], v[96:99]
	v_mfma_f32_16x16x32_bf16 v[84:87], v[184:187], v[216:219], v[84:87]
	v_mfma_f32_16x16x32_bf16 v[80:83], v[192:195], v[216:219], v[80:83]
	v_mfma_f32_16x16x32_bf16 v[68:71], v[184:187], v[224:227], v[68:71]
	v_mfma_f32_16x16x32_bf16 v[64:67], v[192:195], v[224:227], v[64:67]
	s_setprio 0
	s_barrier
; #define PG8_STAGE(bufoff, gbase, voff) do { _Pragma("unroll") for (int _i = 0; _i < 2; ++_i) \
;         __builtin_amdgcn_global_load_lds((const unsigned*)((const char*)(gbase) + (voff)[_i]), (PG8_LAS unsigned*)(lds + (bufoff) + ldsw + _i * 8192), 16, 0, 0); } while (0)
; #define PG8_LDA(dst, b, h) do { _Pragma("unroll") for (int m = 0; m < 4; ++m) _Pragma("unroll") for (int k = 0; k < 2; ++k) dst[m][k] = *(const PG8_LAS bf16x8*)(lds + PG8_SA(b, h) + aoff + m * 2048 + k * 1024); } while (0)
; #define PG8_MMA(ai, bj, At, Bt) do { __builtin_amdgcn_s_setprio(1); _Pragma("unroll") for (int m = 0; m < 4; ++m) _Pragma("unroll") for (int n = 0; n < 2; ++n) _Pragma("unroll") for (int k = 0; k < 2; ++k) \
;         acc[ai][bj][m][n] = __builtin_amdgcn_mfma_f32_16x16x32_bf16(Bt[n][k], At[m][k], acc[ai][bj][m][n], 0, 0, 0); __builtin_amdgcn_s_setprio(0); } while (0)
; #define PG8_WAIT_V(n) asm volatile("s_waitcnt vmcnt(" #n ")" ::: "memory")
; #define PG8_WAIT_L(n) asm volatile("s_waitcnt lgkmcnt(" #n ")" ::: "memory")
; #define PG8_BAR __builtin_amdgcn_s_barrier()
; #define PG8_SCHED __builtin_amdgcn_sched_barrier(0)
; template <class Epi, class Sched, bool ALIGN_EPI = false, bool SP2 = false, bool ABLK = false>
; __device__ __forceinline__ void gemm_phase(PG8_LAS unsigned char* lds, const Gemm g, const Sched& S, const Epi& E) {
;     ...
;             PG8_WAIT_V(8); PG8_WAIT_L(0); PG8_BAR; PG8_MMA(0, 0, At, B0); PG8_MMA(0, 1, At, B1); PG8_BAR; PG8_SCHED;
;             PG8_LDA(At, 1, 1); PG8_STAGE(PG8_SB(1, 0), b3, voffB); PG8_STAGE(PG8_SB(1, 1), b3 + hstep, voffB); PG8_STAGE(PG8_SA(1, 0), a3, voffA);
;             PG8_WAIT_V(8); PG8_WAIT_L(0); PG8_BAR; PG8_MMA(1, 0, At, B0); PG8_MMA(1, 1, At, B1); PG8_BAR; PG8_SCHED;
	s_add_i32 s11, s11, s54
	v_lshl_add_u64 v[228:229], v[228:229], 0, s[30:31]
	s_mov_b32 m0, s11
	ds_read_b128 v[196:199], v164 offset:49152
	ds_read_b128 v[200:203], v164 offset:50176
	ds_read_b128 v[204:207], v164 offset:51200
	ds_read_b128 v[208:211], v164 offset:52224
	ds_read_b128 v[212:215], v164 offset:53248
	ds_read_b128 v[216:219], v164 offset:54272
	ds_read_b128 v[220:223], v164 offset:55296
	ds_read_b128 v[224:227], v164 offset:56320
	global_load_lds_dwordx4 v[228:229], off
	s_add_i32 m0, s11, 0x2000
	s_add_u32 s14, s50, 0x40080
	v_lshl_add_u64 v[228:229], v[230:231], 0, s[30:31]
	s_addc_u32 s15, s51, 0
	s_add_i32 s11, s16, s54
	global_load_lds_dwordx4 v[228:229], off
	v_lshl_add_u64 v[228:229], s[14:15], 0, v[132:133]
	s_mov_b32 m0, s11
	s_nop 0
	global_load_lds_dwordx4 v[228:229], off
	v_lshl_add_u64 v[228:229], s[14:15], 0, v[128:129]
	s_add_i32 m0, s11, 0x2000
	s_nop 0
	global_load_lds_dwordx4 v[228:229], off
	v_lshl_add_u64 v[228:229], v[232:233], 0, s[30:31]
	s_mov_b32 m0, s68
	s_nop 0
	global_load_lds_dwordx4 v[228:229], off
	v_lshl_add_u64 v[228:229], v[234:235], 0, s[30:31]
	s_mov_b32 m0, s69
	s_nop 0
	global_load_lds_dwordx4 v[228:229], off
	s_waitcnt vmcnt(8)
	s_waitcnt lgkmcnt(0)
	s_barrier
	s_setprio 1
	s_waitcnt lgkmcnt(0)
	v_mfma_f32_16x16x32_bf16 v[60:63], v[156:159], v[196:199], v[60:63]
	v_mfma_f32_16x16x32_bf16 v[56:59], v[172:175], v[196:199], v[56:59]
	v_mfma_f32_16x16x32_bf16 v[44:47], v[156:159], v[204:207], v[44:47]
	v_mfma_f32_16x16x32_bf16 v[40:43], v[172:175], v[204:207], v[40:43]
	v_mfma_f32_16x16x32_bf16 v[28:31], v[156:159], v[212:215], v[28:31]
	v_mfma_f32_16x16x32_bf16 v[24:27], v[172:175], v[212:215], v[24:27]
	v_mfma_f32_16x16x32_bf16 v[12:15], v[156:159], v[220:223], v[12:15]
	v_mfma_f32_16x16x32_bf16 v[8:11], v[172:175], v[220:223], v[8:11]
	v_mfma_f32_16x16x32_bf16 v[60:63], v[168:171], v[200:203], v[60:63]
	v_mfma_f32_16x16x32_bf16 v[56:59], v[176:179], v[200:203], v[56:59]
	v_mfma_f32_16x16x32_bf16 v[44:47], v[168:171], v[208:211], v[44:47]
	v_mfma_f32_16x16x32_bf16 v[40:43], v[176:179], v[208:211], v[40:43]
	v_mfma_f32_16x16x32_bf16 v[28:31], v[168:171], v[216:219], v[28:31]
	v_mfma_f32_16x16x32_bf16 v[24:27], v[176:179], v[216:219], v[24:27]
	v_mfma_f32_16x16x32_bf16 v[12:15], v[168:171], v[224:227], v[12:15]
	v_mfma_f32_16x16x32_bf16 v[8:11], v[176:179], v[224:227], v[8:11]
	s_setprio 0
	s_setprio 1
	v_mfma_f32_16x16x32_bf16 v[52:55], v[180:183], v[196:199], v[52:55]
	v_mfma_f32_16x16x32_bf16 v[48:51], v[188:191], v[196:199], v[48:51]
	v_mfma_f32_16x16x32_bf16 v[36:39], v[180:183], v[204:207], v[36:39]
	v_mfma_f32_16x16x32_bf16 v[32:35], v[188:191], v[204:207], v[32:35]
	v_mfma_f32_16x16x32_bf16 v[20:23], v[180:183], v[212:215], v[20:23]
	v_mfma_f32_16x16x32_bf16 v[16:19], v[188:191], v[212:215], v[16:19]
	v_mfma_f32_16x16x32_bf16 v[4:7], v[180:183], v[220:223], v[4:7]
	v_mfma_f32_16x16x32_bf16 v[0:3], v[188:191], v[220:223], v[0:3]
	v_mfma_f32_16x16x32_bf16 v[52:55], v[184:187], v[200:203], v[52:55]
	v_mfma_f32_16x16x32_bf16 v[48:51], v[192:195], v[200:203], v[48:51]
	v_mfma_f32_16x16x32_bf16 v[36:39], v[184:187], v[208:211], v[36:39]
	v_mfma_f32_16x16x32_bf16 v[32:35], v[192:195], v[208:211], v[32:35]
	v_mfma_f32_16x16x32_bf16 v[20:23], v[184:187], v[216:219], v[20:23]
	v_mfma_f32_16x16x32_bf16 v[16:19], v[192:195], v[216:219], v[16:19]
	v_mfma_f32_16x16x32_bf16 v[4:7], v[184:187], v[224:227], v[4:7]
	v_mfma_f32_16x16x32_bf16 v[0:3], v[192:195], v[224:227], v[0:3]
	s_setprio 0
	s_barrier
	s_add_i32 s10, s10, 2
	s_add_u32 s36, s36, 0x100
	s_addc_u32 s37, s37, 0
	s_add_u32 s8, s8, 0x100
	s_addc_u32 s9, s9, 0
	s_cmp_gt_u32 s10, 13
	s_cbranch_scc1 .Lpeel_post_3

; #define PG8_STAGE(bufoff, gbase, voff) do { _Pragma("unroll") for (int _i = 0; _i < 2; ++_i) \
;         __builtin_amdgcn_global_load_lds((const unsigned*)((const char*)(gbase) + (voff)[_i]), (PG8_LAS unsigned*)(lds + (bufoff) + ldsw + _i * 8192), 16, 0, 0); } while (0)
; #define PG8_LDA(dst, b, h) do { _Pragma("unroll") for (int m = 0; m < 4; ++m) _Pragma("unroll") for (int k = 0; k < 2; ++k) dst[m][k] = *(const PG8_LAS bf16x8*)(lds + PG8_SA(b, h) + aoff + m * 2048 + k * 1024); } while (0)
; #define PG8_LDB(dst, b, h) do { _Pragma("unroll") for (int n = 0; n < 2; ++n) _Pragma("unroll") for (int k = 0; k < 2; ++k) dst[n][k] = *(const PG8_LAS bf16x8*)(lds + PG8_SB(b, h) + boff + n * 2048 + k * 1024); } while (0)
; #define PG8_MMA(ai, bj, At, Bt) do { __builtin_amdgcn_s_setprio(1); _Pragma("unroll") for (int m = 0; m < 4; ++m) _Pragma("unroll") for (int n = 0; n < 2; ++n) _Pragma("unroll") for (int k = 0; k < 2; ++k) \
;         acc[ai][bj][m][n] = __builtin_amdgcn_mfma_f32_16x16x32_bf16(Bt[n][k], At[m][k], acc[ai][bj][m][n], 0, 0, 0); __builtin_amdgcn_s_setprio(0); } while (0)
; #define PG8_WAIT_V(n) asm volatile("s_waitcnt vmcnt(" #n ")" ::: "memory")
; #define PG8_WAIT_L(n) asm volatile("s_waitcnt lgkmcnt(" #n ")" ::: "memory")
; #define PG8_BAR __builtin_amdgcn_s_barrier()
; #define PG8_SCHED __builtin_amdgcn_sched_barrier(0)
; template <class Epi, class Sched, bool ALIGN_EPI = false, bool SP2 = false, bool ABLK = false>
; __device__ __forceinline__ void gemm_phase(PG8_LAS unsigned char* lds, const Gemm g, const Sched& S, const Epi& E) {
;     ...
;             PG8_LDB(B0, 0, 0); PG8_LDB(B1, 0, 1); PG8_SCHED; PG8_LDA(At, 0, 0); PG8_STAGE(PG8_SA(1, 1), a1 + hstepA, voffA);
;             PG8_WAIT_V(8); PG8_WAIT_L(0); PG8_BAR; PG8_MMA(0, 0, At, B0); PG8_MMA(0, 1, At, B1); PG8_BAR; PG8_SCHED;
;             PG8_LDA(At, 0, 1); PG8_STAGE(PG8_SB(0, 0), b2, voffB); PG8_STAGE(PG8_SB(0, 1), b2 + hstep, voffB); PG8_STAGE(PG8_SA(0, 0), a2, voffA);
;             PG8_WAIT_V(8); PG8_WAIT_L(0); PG8_BAR; PG8_MMA(1, 0, At, B0); PG8_MMA(1, 1, At, B1); PG8_BAR; PG8_SCHED;
;     ...
; #pragma unroll
;         for (int a = 0; a < 2; ++a)
; #pragma unroll
;             for (int b = 0; b < 2; ++b)
; #pragma unroll
;                 for (int m = 0; m < 4; ++m)
; #pragma unroll
;                     for (int n = 0; n < 2; ++n) acc[a][b][m][n] = (f32x4){0.f, 0.f, 0.f, 0.f};
.LBB0_905:
	ds_read_b128 v[144:147], v151
	ds_read_b128 v[156:159], v151 offset:1024
	ds_read_b128 v[160:163], v151 offset:2048
	ds_read_b128 v[168:171], v151 offset:3072
	ds_read_b128 v[172:175], v152
	ds_read_b128 v[176:179], v152 offset:1024
	ds_read_b128 v[180:183], v152 offset:2048
	ds_read_b128 v[184:187], v152 offset:3072
	s_add_u32 s16, s44, 0x4000
	s_addc_u32 s17, s45, 0
	s_cmp_eq_u32 s60, 40
	s_cselect_b32 s50, s0, s16
	s_cselect_b32 s51, s1, s17
	s_cselect_b32 s48, s42, s14
	s_cselect_b32 s49, s43, s15
	s_add_u32 s46, s50, 0x8000
	s_addc_u32 s47, s51, 0
	v_lshl_add_u64 v[164:165], s[44:45], 0, v[136:137]
	s_add_i32 m0, s7, 0xc000
	ds_read_b128 v[188:191], v153
	ds_read_b128 v[192:195], v153 offset:1024
	ds_read_b128 v[196:199], v153 offset:2048
	ds_read_b128 v[200:203], v153 offset:3072
	ds_read_b128 v[204:207], v153 offset:4096
	ds_read_b128 v[208:211], v153 offset:5120
	ds_read_b128 v[212:215], v153 offset:6144
	ds_read_b128 v[216:219], v153 offset:7168
	global_load_lds_dwordx4 v[164:165], off
	v_lshl_add_u64 v[164:165], s[44:45], 0, v[138:139]
	s_add_i32 m0, s7, 0xe000
	s_nop 0
	global_load_lds_dwordx4 v[164:165], off
	s_waitcnt vmcnt(8)
	s_waitcnt lgkmcnt(0)
	s_barrier
	s_setprio 1
	s_waitcnt lgkmcnt(0)
	v_mfma_f32_16x16x32_bf16 v[124:127], v[144:147], v[188:191], 0
	v_mfma_f32_16x16x32_bf16 v[120:123], v[160:163], v[188:191], 0
	v_mfma_f32_16x16x32_bf16 v[108:111], v[144:147], v[196:199], 0
	v_mfma_f32_16x16x32_bf16 v[104:107], v[160:163], v[196:199], 0
	v_mfma_f32_16x16x32_bf16 v[92:95], v[144:147], v[204:207], 0
	v_mfma_f32_16x16x32_bf16 v[88:91], v[160:163], v[204:207], 0
	v_mfma_f32_16x16x32_bf16 v[76:79], v[144:147], v[212:215], 0
	v_mfma_f32_16x16x32_bf16 v[72:75], v[160:163], v[212:215], 0
	v_mfma_f32_16x16x32_bf16 v[124:127], v[156:159], v[192:195], v[124:127]
	v_mfma_f32_16x16x32_bf16 v[120:123], v[168:171], v[192:195], v[120:123]
	v_mfma_f32_16x16x32_bf16 v[108:111], v[156:159], v[200:203], v[108:111]
	v_mfma_f32_16x16x32_bf16 v[104:107], v[168:171], v[200:203], v[104:107]
	v_mfma_f32_16x16x32_bf16 v[92:95], v[156:159], v[208:211], v[92:95]
	v_mfma_f32_16x16x32_bf16 v[88:91], v[168:171], v[208:211], v[88:91]
	v_mfma_f32_16x16x32_bf16 v[76:79], v[156:159], v[216:219], v[76:79]
	v_mfma_f32_16x16x32_bf16 v[72:75], v[168:171], v[216:219], v[72:75]
	s_setprio 0
	s_setprio 1
	v_mfma_f32_16x16x32_bf16 v[116:119], v[172:175], v[188:191], 0
	v_mfma_f32_16x16x32_bf16 v[112:115], v[180:183], v[188:191], 0
	v_mfma_f32_16x16x32_bf16 v[100:103], v[172:175], v[196:199], 0
	v_mfma_f32_16x16x32_bf16 v[96:99], v[180:183], v[196:199], 0
	v_mfma_f32_16x16x32_bf16 v[84:87], v[172:175], v[204:207], 0
	v_mfma_f32_16x16x32_bf16 v[80:83], v[180:183], v[204:207], 0
	v_mfma_f32_16x16x32_bf16 v[68:71], v[172:175], v[212:215], 0
	v_mfma_f32_16x16x32_bf16 v[64:67], v[180:183], v[212:215], 0
	v_mfma_f32_16x16x32_bf16 v[116:119], v[176:179], v[192:195], v[116:119]
	v_mfma_f32_16x16x32_bf16 v[112:115], v[184:187], v[192:195], v[112:115]
	v_mfma_f32_16x16x32_bf16 v[100:103], v[176:179], v[200:203], v[100:103]
	v_mfma_f32_16x16x32_bf16 v[96:99], v[184:187], v[200:203], v[96:99]
	v_mfma_f32_16x16x32_bf16 v[84:87], v[176:179], v[208:211], v[84:87]
	v_mfma_f32_16x16x32_bf16 v[80:83], v[184:187], v[208:211], v[80:83]
	v_mfma_f32_16x16x32_bf16 v[68:71], v[176:179], v[216:219], v[68:71]
	v_mfma_f32_16x16x32_bf16 v[64:67], v[184:187], v[216:219], v[64:67]
	s_setprio 0
	s_barrier
	s_add_i32 s16, s54, s4
	v_lshl_add_u64 v[164:165], s[48:49], 0, v[130:131]
	s_mov_b32 m0, s16
	ds_read_b128 v[188:191], v153 offset:16384
	ds_read_b128 v[192:195], v153 offset:17408
	ds_read_b128 v[196:199], v153 offset:18432
	ds_read_b128 v[200:203], v153 offset:19456
	ds_read_b128 v[204:207], v153 offset:20480
	ds_read_b128 v[208:211], v153 offset:21504
	ds_read_b128 v[212:215], v153 offset:22528
	ds_read_b128 v[216:219], v153 offset:23552
	global_load_lds_dwordx4 v[164:165], off
	s_add_i32 m0, s16, 0x2000
	s_add_u32 s16, s48, 0xb0000
	v_lshl_add_u64 v[220:221], s[48:49], 0, v[134:135]
	s_addc_u32 s17, s49, 0
	s_add_i32 s18, s55, s4
	global_load_lds_dwordx4 v[220:221], off
	v_lshl_add_u64 v[222:223], s[16:17], 0, v[130:131]
	s_mov_b32 m0, s18
	s_nop 0
	global_load_lds_dwordx4 v[222:223], off
	v_lshl_add_u64 v[222:223], s[16:17], 0, v[134:135]
	s_add_i32 m0, s18, 0x2000
	s_nop 0
	global_load_lds_dwordx4 v[222:223], off
	v_lshl_add_u64 v[222:223], s[50:51], 0, v[128:129]
	s_mov_b32 m0, s7
	s_nop 0
	global_load_lds_dwordx4 v[222:223], off
	v_lshl_add_u64 v[222:223], s[50:51], 0, v[132:133]
	s_mov_b32 m0, s8
	s_nop 0
	global_load_lds_dwordx4 v[222:223], off
	s_waitcnt vmcnt(8)
	s_waitcnt lgkmcnt(0)
	s_barrier
; #define PG8_STAGE(bufoff, gbase, voff) do { _Pragma("unroll") for (int _i = 0; _i < 2; ++_i) \
;         __builtin_amdgcn_global_load_lds((const unsigned*)((const char*)(gbase) + (voff)[_i]), (PG8_LAS unsigned*)(lds + (bufoff) + ldsw + _i * 8192), 16, 0, 0); } while (0)
; #define PG8_LDA(dst, b, h) do { _Pragma("unroll") for (int m = 0; m < 4; ++m) _Pragma("unroll") for (int k = 0; k < 2; ++k) dst[m][k] = *(const PG8_LAS bf16x8*)(lds + PG8_SA(b, h) + aoff + m * 2048 + k * 1024); } while (0)
; #define PG8_LDB(dst, b, h) do { _Pragma("unroll") for (int n = 0; n < 2; ++n) _Pragma("unroll") for (int k = 0; k < 2; ++k) dst[n][k] = *(const PG8_LAS bf16x8*)(lds + PG8_SB(b, h) + boff + n * 2048 + k * 1024); } while (0)
; #define PG8_MMA(ai, bj, At, Bt) do { __builtin_amdgcn_s_setprio(1); _Pragma("unroll") for (int m = 0; m < 4; ++m) _Pragma("unroll") for (int n = 0; n < 2; ++n) _Pragma("unroll") for (int k = 0; k < 2; ++k) \
;         acc[ai][bj][m][n] = __builtin_amdgcn_mfma_f32_16x16x32_bf16(Bt[n][k], At[m][k], acc[ai][bj][m][n], 0, 0, 0); __builtin_amdgcn_s_setprio(0); } while (0)
; #define PG8_WAIT_V(n) asm volatile("s_waitcnt vmcnt(" #n ")" ::: "memory")
; #define PG8_WAIT_L(n) asm volatile("s_waitcnt lgkmcnt(" #n ")" ::: "memory")
; #define PG8_BAR __builtin_amdgcn_s_barrier()
; #define PG8_SCHED __builtin_amdgcn_sched_barrier(0)
; template <class Epi, class Sched, bool ALIGN_EPI = false, bool SP2 = false, bool ABLK = false>
; __device__ __forceinline__ void gemm_phase(PG8_LAS unsigned char* lds, const Gemm g, const Sched& S, const Epi& E) {
;     ...
;             PG8_WAIT_V(8); PG8_WAIT_L(0); PG8_BAR; PG8_MMA(1, 0, At, B0); PG8_MMA(1, 1, At, B1); PG8_BAR; PG8_SCHED;
;             PG8_LDB(B0, 1, 0); PG8_LDB(B1, 1, 1); PG8_SCHED; PG8_LDA(At, 1, 0); PG8_STAGE(PG8_SA(0, 1), a2 + hstepA, voffA);
;             PG8_WAIT_V(8); PG8_WAIT_L(0); PG8_BAR; PG8_MMA(0, 0, At, B0); PG8_MMA(0, 1, At, B1); PG8_BAR; PG8_SCHED;
	s_setprio 1
	s_waitcnt lgkmcnt(0)
	v_mfma_f32_16x16x32_bf16 v[60:63], v[144:147], v[188:191], 0
	v_mfma_f32_16x16x32_bf16 v[56:59], v[160:163], v[188:191], 0
	v_mfma_f32_16x16x32_bf16 v[44:47], v[144:147], v[196:199], 0
	v_mfma_f32_16x16x32_bf16 v[40:43], v[160:163], v[196:199], 0
	v_mfma_f32_16x16x32_bf16 v[28:31], v[144:147], v[204:207], 0
	v_mfma_f32_16x16x32_bf16 v[24:27], v[160:163], v[204:207], 0
	v_mfma_f32_16x16x32_bf16 v[12:15], v[144:147], v[212:215], 0
	v_mfma_f32_16x16x32_bf16 v[8:11], v[160:163], v[212:215], 0
	v_mfma_f32_16x16x32_bf16 v[60:63], v[156:159], v[192:195], v[60:63]
	v_mfma_f32_16x16x32_bf16 v[56:59], v[168:171], v[192:195], v[56:59]
	v_mfma_f32_16x16x32_bf16 v[44:47], v[156:159], v[200:203], v[44:47]
	v_mfma_f32_16x16x32_bf16 v[40:43], v[168:171], v[200:203], v[40:43]
	v_mfma_f32_16x16x32_bf16 v[28:31], v[156:159], v[208:211], v[28:31]
	v_mfma_f32_16x16x32_bf16 v[24:27], v[168:171], v[208:211], v[24:27]
	v_mfma_f32_16x16x32_bf16 v[12:15], v[156:159], v[216:219], v[12:15]
	v_mfma_f32_16x16x32_bf16 v[8:11], v[168:171], v[216:219], v[8:11]
	s_setprio 0
	s_setprio 1
	v_mfma_f32_16x16x32_bf16 v[52:55], v[172:175], v[188:191], 0
	v_mfma_f32_16x16x32_bf16 v[48:51], v[180:183], v[188:191], 0
	v_mfma_f32_16x16x32_bf16 v[36:39], v[172:175], v[196:199], 0
	v_mfma_f32_16x16x32_bf16 v[32:35], v[180:183], v[196:199], 0
	v_mfma_f32_16x16x32_bf16 v[20:23], v[172:175], v[204:207], 0
	v_mfma_f32_16x16x32_bf16 v[16:19], v[180:183], v[204:207], 0
	v_mfma_f32_16x16x32_bf16 v[4:7], v[172:175], v[212:215], 0
	v_mfma_f32_16x16x32_bf16 v[0:3], v[180:183], v[212:215], 0
	v_mfma_f32_16x16x32_bf16 v[52:55], v[176:179], v[192:195], v[52:55]
	v_mfma_f32_16x16x32_bf16 v[48:51], v[184:187], v[192:195], v[48:51]
	v_mfma_f32_16x16x32_bf16 v[36:39], v[176:179], v[200:203], v[36:39]
	v_mfma_f32_16x16x32_bf16 v[32:35], v[184:187], v[200:203], v[32:35]
	v_mfma_f32_16x16x32_bf16 v[20:23], v[176:179], v[208:211], v[20:23]
	v_mfma_f32_16x16x32_bf16 v[16:19], v[184:187], v[208:211], v[16:19]
	v_mfma_f32_16x16x32_bf16 v[4:7], v[176:179], v[216:219], v[4:7]
	v_mfma_f32_16x16x32_bf16 v[0:3], v[184:187], v[216:219], v[0:3]
	s_setprio 0
	s_barrier
	s_add_i32 s18, 0, 0x18000
	v_add_u32_e32 v155, s18, v149
	s_add_i32 s19, 0, 0x1c000
	ds_read_b128 v[144:147], v155
	ds_read_b128 v[156:159], v155 offset:1024
	ds_read_b128 v[160:163], v155 offset:2048
	ds_read_b128 v[168:171], v155 offset:3072
	v_add_u32_e32 v155, s19, v149
	ds_read_b128 v[172:175], v155
	ds_read_b128 v[176:179], v155 offset:1024
	ds_read_b128 v[180:183], v155 offset:2048
	ds_read_b128 v[184:187], v155 offset:3072
	s_add_u32 s16, s50, 0x4000
	s_addc_u32 s17, s51, 0
	s_mov_b32 m0, s9
	v_lshl_add_u64 v[222:223], s[16:17], 0, v[128:129]
	ds_read_b128 v[188:191], v153 offset:32768
	ds_read_b128 v[192:195], v153 offset:33792
	ds_read_b128 v[196:199], v153 offset:34816
	ds_read_b128 v[200:203], v153 offset:35840
	ds_read_b128 v[204:207], v153 offset:36864
	ds_read_b128 v[208:211], v153 offset:37888
	ds_read_b128 v[212:215], v153 offset:38912
	ds_read_b128 v[216:219], v153 offset:39936
	global_load_lds_dwordx4 v[222:223], off
	v_lshl_add_u64 v[222:223], s[16:17], 0, v[132:133]
	s_mov_b32 m0, s10
	s_nop 0
	global_load_lds_dwordx4 v[222:223], off
	s_waitcnt vmcnt(8)
	s_waitcnt lgkmcnt(0)
	s_barrier
	s_setprio 1
	s_waitcnt lgkmcnt(0)
	v_mfma_f32_16x16x32_bf16 v[124:127], v[144:147], v[188:191], v[124:127]
	v_mfma_f32_16x16x32_bf16 v[120:123], v[160:163], v[188:191], v[120:123]
	v_mfma_f32_16x16x32_bf16 v[108:111], v[144:147], v[196:199], v[108:111]
	v_mfma_f32_16x16x32_bf16 v[104:107], v[160:163], v[196:199], v[104:107]
	v_mfma_f32_16x16x32_bf16 v[92:95], v[144:147], v[204:207], v[92:95]
	v_mfma_f32_16x16x32_bf16 v[88:91], v[160:163], v[204:207], v[88:91]
	v_mfma_f32_16x16x32_bf16 v[76:79], v[144:147], v[212:215], v[76:79]
	v_mfma_f32_16x16x32_bf16 v[72:75], v[160:163], v[212:215], v[72:75]
	v_mfma_f32_16x16x32_bf16 v[124:127], v[156:159], v[192:195], v[124:127]
	v_mfma_f32_16x16x32_bf16 v[120:123], v[168:171], v[192:195], v[120:123]
	v_mfma_f32_16x16x32_bf16 v[108:111], v[156:159], v[200:203], v[108:111]
	v_mfma_f32_16x16x32_bf16 v[104:107], v[168:171], v[200:203], v[104:107]
	v_mfma_f32_16x16x32_bf16 v[92:95], v[156:159], v[208:211], v[92:95]
	v_mfma_f32_16x16x32_bf16 v[88:91], v[168:171], v[208:211], v[88:91]
	v_mfma_f32_16x16x32_bf16 v[76:79], v[156:159], v[216:219], v[76:79]
	v_mfma_f32_16x16x32_bf16 v[72:75], v[168:171], v[216:219], v[72:75]
	s_setprio 0
	s_setprio 1
	v_mfma_f32_16x16x32_bf16 v[116:119], v[172:175], v[188:191], v[116:119]
	v_mfma_f32_16x16x32_bf16 v[112:115], v[180:183], v[188:191], v[112:115]
	v_mfma_f32_16x16x32_bf16 v[100:103], v[172:175], v[196:199], v[100:103]
	v_mfma_f32_16x16x32_bf16 v[96:99], v[180:183], v[196:199], v[96:99]
	v_mfma_f32_16x16x32_bf16 v[84:87], v[172:175], v[204:207], v[84:87]
	v_mfma_f32_16x16x32_bf16 v[80:83], v[180:183], v[204:207], v[80:83]
	v_mfma_f32_16x16x32_bf16 v[68:71], v[172:175], v[212:215], v[68:71]
	v_mfma_f32_16x16x32_bf16 v[64:67], v[180:183], v[212:215], v[64:67]
	v_mfma_f32_16x16x32_bf16 v[116:119], v[176:179], v[192:195], v[116:119]
	v_mfma_f32_16x16x32_bf16 v[112:115], v[184:187], v[192:195], v[112:115]
	v_mfma_f32_16x16x32_bf16 v[100:103], v[176:179], v[200:203], v[100:103]
	v_mfma_f32_16x16x32_bf16 v[96:99], v[184:187], v[200:203], v[96:99]
	v_mfma_f32_16x16x32_bf16 v[84:87], v[176:179], v[208:211], v[84:87]
	v_mfma_f32_16x16x32_bf16 v[80:83], v[184:187], v[208:211], v[80:83]
	v_mfma_f32_16x16x32_bf16 v[68:71], v[176:179], v[216:219], v[68:71]
	v_mfma_f32_16x16x32_bf16 v[64:67], v[184:187], v[216:219], v[64:67]
	s_setprio 0
	s_barrier
; #define PG8_STAGE(bufoff, gbase, voff) do { _Pragma("unroll") for (int _i = 0; _i < 2; ++_i) \
;         __builtin_amdgcn_global_load_lds((const unsigned*)((const char*)(gbase) + (voff)[_i]), (PG8_LAS unsigned*)(lds + (bufoff) + ldsw + _i * 8192), 16, 0, 0); } while (0)
; #define PG8_LDA(dst, b, h) do { _Pragma("unroll") for (int m = 0; m < 4; ++m) _Pragma("unroll") for (int k = 0; k < 2; ++k) dst[m][k] = *(const PG8_LAS bf16x8*)(lds + PG8_SA(b, h) + aoff + m * 2048 + k * 1024); } while (0)
; #define PG8_MMA(ai, bj, At, Bt) do { __builtin_amdgcn_s_setprio(1); _Pragma("unroll") for (int m = 0; m < 4; ++m) _Pragma("unroll") for (int n = 0; n < 2; ++n) _Pragma("unroll") for (int k = 0; k < 2; ++k) \
;         acc[ai][bj][m][n] = __builtin_amdgcn_mfma_f32_16x16x32_bf16(Bt[n][k], At[m][k], acc[ai][bj][m][n], 0, 0, 0); __builtin_amdgcn_s_setprio(0); } while (0)
; #define PG8_WAIT_V(n) asm volatile("s_waitcnt vmcnt(" #n ")" ::: "memory")
; #define PG8_WAIT_L(n) asm volatile("s_waitcnt lgkmcnt(" #n ")" ::: "memory")
; #define PG8_BAR __builtin_amdgcn_s_barrier()
; #define PG8_SCHED __builtin_amdgcn_sched_barrier(0)
; template <class Epi, class Sched, bool ALIGN_EPI = false, bool SP2 = false, bool ABLK = false>
; __device__ __forceinline__ void gemm_phase(PG8_LAS unsigned char* lds, const Gemm g, const Sched& S, const Epi& E) {
;     ...
;             PG8_WAIT_V(8); PG8_WAIT_L(0); PG8_BAR; PG8_MMA(0, 0, At, B0); PG8_MMA(0, 1, At, B1); PG8_BAR; PG8_SCHED;
;             PG8_LDA(At, 1, 1); PG8_STAGE(PG8_SB(1, 0), b3, voffB); PG8_STAGE(PG8_SB(1, 1), b3 + hstep, voffB); PG8_STAGE(PG8_SA(1, 0), a3, voffA);
;             PG8_WAIT_V(8); PG8_WAIT_L(0); PG8_BAR; PG8_MMA(1, 0, At, B0); PG8_MMA(1, 1, At, B1); PG8_BAR; PG8_SCHED;
	s_add_i32 s16, s18, s4
	v_lshl_add_u64 v[164:165], v[164:165], 0, s[30:31]
	s_mov_b32 m0, s16
	ds_read_b128 v[188:191], v153 offset:49152
	ds_read_b128 v[192:195], v153 offset:50176
	ds_read_b128 v[196:199], v153 offset:51200
	ds_read_b128 v[200:203], v153 offset:52224
	ds_read_b128 v[204:207], v153 offset:53248
	ds_read_b128 v[208:211], v153 offset:54272
	ds_read_b128 v[212:215], v153 offset:55296
	ds_read_b128 v[216:219], v153 offset:56320
	global_load_lds_dwordx4 v[164:165], off
	s_add_i32 m0, s16, 0x2000
	s_add_u32 s16, s48, 0xb0080
	v_lshl_add_u64 v[164:165], v[220:221], 0, s[30:31]
	s_addc_u32 s17, s49, 0
	s_add_i32 s18, s19, s4
	global_load_lds_dwordx4 v[164:165], off
	v_lshl_add_u64 v[164:165], s[16:17], 0, v[130:131]
	s_mov_b32 m0, s18
	s_nop 0
	global_load_lds_dwordx4 v[164:165], off
	v_lshl_add_u64 v[164:165], s[16:17], 0, v[134:135]
	s_add_i32 m0, s18, 0x2000
	s_nop 0
	global_load_lds_dwordx4 v[164:165], off
	v_lshl_add_u64 v[164:165], s[46:47], 0, v[128:129]
	s_mov_b32 m0, s52
	s_nop 0
	global_load_lds_dwordx4 v[164:165], off
	v_lshl_add_u64 v[164:165], s[46:47], 0, v[132:133]
	s_mov_b32 m0, s53
	s_nop 0
	global_load_lds_dwordx4 v[164:165], off
	s_waitcnt vmcnt(8)
	s_waitcnt lgkmcnt(0)
	s_barrier
	s_setprio 1
	s_waitcnt lgkmcnt(0)
	v_mfma_f32_16x16x32_bf16 v[60:63], v[144:147], v[188:191], v[60:63]
	v_mfma_f32_16x16x32_bf16 v[56:59], v[160:163], v[188:191], v[56:59]
	v_mfma_f32_16x16x32_bf16 v[44:47], v[144:147], v[196:199], v[44:47]
	v_mfma_f32_16x16x32_bf16 v[40:43], v[160:163], v[196:199], v[40:43]
	v_mfma_f32_16x16x32_bf16 v[28:31], v[144:147], v[204:207], v[28:31]
	v_mfma_f32_16x16x32_bf16 v[24:27], v[160:163], v[204:207], v[24:27]
	v_mfma_f32_16x16x32_bf16 v[12:15], v[144:147], v[212:215], v[12:15]
	v_mfma_f32_16x16x32_bf16 v[8:11], v[160:163], v[212:215], v[8:11]
	v_mfma_f32_16x16x32_bf16 v[60:63], v[156:159], v[192:195], v[60:63]
	v_mfma_f32_16x16x32_bf16 v[56:59], v[168:171], v[192:195], v[56:59]
	v_mfma_f32_16x16x32_bf16 v[44:47], v[156:159], v[200:203], v[44:47]
	v_mfma_f32_16x16x32_bf16 v[40:43], v[168:171], v[200:203], v[40:43]
	v_mfma_f32_16x16x32_bf16 v[28:31], v[156:159], v[208:211], v[28:31]
	v_mfma_f32_16x16x32_bf16 v[24:27], v[168:171], v[208:211], v[24:27]
	v_mfma_f32_16x16x32_bf16 v[12:15], v[156:159], v[216:219], v[12:15]
	v_mfma_f32_16x16x32_bf16 v[8:11], v[168:171], v[216:219], v[8:11]
	s_setprio 0
	s_setprio 1
	v_mfma_f32_16x16x32_bf16 v[52:55], v[172:175], v[188:191], v[52:55]
	v_mfma_f32_16x16x32_bf16 v[48:51], v[180:183], v[188:191], v[48:51]
	v_mfma_f32_16x16x32_bf16 v[36:39], v[172:175], v[196:199], v[36:39]
	v_mfma_f32_16x16x32_bf16 v[32:35], v[180:183], v[196:199], v[32:35]
	v_mfma_f32_16x16x32_bf16 v[20:23], v[172:175], v[204:207], v[20:23]
	v_mfma_f32_16x16x32_bf16 v[16:19], v[180:183], v[204:207], v[16:19]
	v_mfma_f32_16x16x32_bf16 v[4:7], v[172:175], v[212:215], v[4:7]
	v_mfma_f32_16x16x32_bf16 v[0:3], v[180:183], v[212:215], v[0:3]
	v_mfma_f32_16x16x32_bf16 v[52:55], v[176:179], v[192:195], v[52:55]
	v_mfma_f32_16x16x32_bf16 v[48:51], v[184:187], v[192:195], v[48:51]
	v_mfma_f32_16x16x32_bf16 v[36:39], v[176:179], v[200:203], v[36:39]
	v_mfma_f32_16x16x32_bf16 v[32:35], v[184:187], v[200:203], v[32:35]
	v_mfma_f32_16x16x32_bf16 v[20:23], v[176:179], v[208:211], v[20:23]
	v_mfma_f32_16x16x32_bf16 v[16:19], v[184:187], v[208:211], v[16:19]
	v_mfma_f32_16x16x32_bf16 v[4:7], v[176:179], v[216:219], v[4:7]
	v_mfma_f32_16x16x32_bf16 v[0:3], v[184:187], v[216:219], v[0:3]
	s_setprio 0
	s_barrier
	s_add_i32 s60, s60, 2
	s_add_u32 s14, s14, 0x100
	s_addc_u32 s15, s15, 0
	s_add_u32 s44, s44, 0x10000
	s_addc_u32 s45, s45, 0
	s_cmp_gt_u32 s60, 41
	s_cbranch_scc1 .Lpeel_post_4
